# activation epilogues (HG in-proj, W1): packed f32 fma/mul/add and a DPP select for the lane-pair exchange (same arithmetic, ~25% fewer VALU instructions)
# speedup vs baseline: 1.0115x; 1.0072x over previous
.LBB0_274:
	s_ashr_i32 s23, s34, 2
	s_lshl_b32 s86, s35, 11
	s_add_i32 s86, s86, 0x20400
	s_lshl_b32 s87, s4, 2
	s_add_i32 s87, s86, s87
	v_lshl_add_u32 v173, v209, 2, s87
	ds_read_b32 v172, v173 offset:0
	ds_read_b32 v174, v173 offset:64
	ds_read_b32 v176, v173 offset:128
	ds_read_b32 v178, v173 offset:192
	ds_read_b32 v180, v173 offset:512
	ds_read_b32 v182, v173 offset:576
	ds_read_b32 v188, v173 offset:640
	ds_read_b32 v240, v173 offset:704
	s_lshl_b32 s87, s43, 2
	s_add_i32 s87, s86, s87
	v_lshl_add_u32 v173, v211, 2, s87
	ds_read_b128 v[26:29], v173 offset:1024
	ds_read_b128 v[30:33], v173 offset:1040
	ds_read_b128 v[42:45], v173 offset:1536
	ds_read_b128 v[46:49], v173 offset:1552
	s_mov_b32 s62, 0xaaaaaaaa
	s_mov_b32 s63, 0xaaaaaaaa
	s_mov_b32 s84, 0x55555555
	s_mov_b32 s85, 0x55555555
	v_and_b32_e32 v181, 1, v209
	v_lshl_or_b32 v189, s43, 1, v211
	v_lshl_or_b32 v189, s34, 8, v189
	v_lshl_add_u32 v177, v181, 5, v189
	v_lshl_add_u32 v173, s48, 8, v210
	v_sub_u32_e32 v173, v173, v181
	v_lshlrev_b32_e32 v173, 13, v173
	v_lshl_add_u32 v177, v177, 1, v173
	s_mov_b32 s88, 0xbfb8aa3b
	s_mov_b32 s90, 0x3fb8aa3b
	s_cmp_eq_u32 s23, 1
	s_cbranch_scc1 .Lact1_hgin_kk
	s_cmp_eq_u32 s23, 2
	s_cbranch_scc1 .Lact1_hgin_id
	s_waitcnt lgkmcnt(0)
	v_pk_fma_f32 v[142:143], v[142:143], v[172:173], v[26:27] op_sel_hi:[1,0,1]
	v_pk_fma_f32 v[144:145], v[144:145], v[172:173], v[28:29] op_sel_hi:[1,0,1]
	v_pk_fma_f32 v[138:139], v[138:139], v[172:173], v[30:31] op_sel_hi:[1,0,1]
	v_pk_fma_f32 v[140:141], v[140:141], v[172:173], v[32:33] op_sel_hi:[1,0,1]
	v_pk_mul_f32 v[216:217], v[142:143], s[88:89] op_sel_hi:[1,0]
	v_pk_mul_f32 v[218:219], v[144:145], s[88:89] op_sel_hi:[1,0]
	v_pk_mul_f32 v[220:221], v[138:139], s[88:89] op_sel_hi:[1,0]
	v_pk_mul_f32 v[222:223], v[140:141], s[88:89] op_sel_hi:[1,0]
	v_exp_f32_e32 v216, v216
	v_exp_f32_e32 v217, v217
	v_exp_f32_e32 v218, v218
	v_exp_f32_e32 v219, v219
	v_exp_f32_e32 v220, v220
	v_exp_f32_e32 v221, v221
	v_exp_f32_e32 v222, v222
	v_exp_f32_e32 v223, v223
	v_pk_add_f32 v[216:217], v[216:217], 1.0 op_sel_hi:[1,0]
	v_pk_add_f32 v[218:219], v[218:219], 1.0 op_sel_hi:[1,0]
	v_pk_add_f32 v[220:221], v[220:221], 1.0 op_sel_hi:[1,0]
	v_pk_add_f32 v[222:223], v[222:223], 1.0 op_sel_hi:[1,0]
	v_rcp_f32_e32 v216, v216
	v_rcp_f32_e32 v217, v217
	v_rcp_f32_e32 v218, v218
	v_rcp_f32_e32 v219, v219
	v_rcp_f32_e32 v220, v220
	v_rcp_f32_e32 v221, v221
	v_rcp_f32_e32 v222, v222
	v_rcp_f32_e32 v223, v223
	v_pk_mul_f32 v[142:143], v[142:143], v[216:217]
	v_pk_mul_f32 v[144:145], v[144:145], v[218:219]
	v_pk_mul_f32 v[138:139], v[138:139], v[220:221]
	v_pk_mul_f32 v[140:141], v[140:141], v[222:223]
	v_cvt_pk_bf16_f32 v168, v142, v143
	v_cvt_pk_bf16_f32 v169, v144, v145
	v_cvt_pk_bf16_f32 v170, v138, v139
	v_cvt_pk_bf16_f32 v171, v140, v141
	v_pk_fma_f32 v[134:135], v[134:135], v[172:173], v[42:43] op_sel_hi:[1,0,1]
	v_pk_fma_f32 v[136:137], v[136:137], v[172:173], v[44:45] op_sel_hi:[1,0,1]
	v_pk_fma_f32 v[130:131], v[130:131], v[172:173], v[46:47] op_sel_hi:[1,0,1]
	v_pk_fma_f32 v[132:133], v[132:133], v[172:173], v[48:49] op_sel_hi:[1,0,1]
	v_pk_mul_f32 v[216:217], v[134:135], s[88:89] op_sel_hi:[1,0]
	v_pk_mul_f32 v[218:219], v[136:137], s[88:89] op_sel_hi:[1,0]
	v_pk_mul_f32 v[220:221], v[130:131], s[88:89] op_sel_hi:[1,0]
	v_pk_mul_f32 v[222:223], v[132:133], s[88:89] op_sel_hi:[1,0]
	v_exp_f32_e32 v216, v216
	v_exp_f32_e32 v217, v217
	v_exp_f32_e32 v218, v218
	v_exp_f32_e32 v219, v219
	v_exp_f32_e32 v220, v220
	v_exp_f32_e32 v221, v221
	v_exp_f32_e32 v222, v222
	v_exp_f32_e32 v223, v223
	v_pk_add_f32 v[216:217], v[216:217], 1.0 op_sel_hi:[1,0]
	v_pk_add_f32 v[218:219], v[218:219], 1.0 op_sel_hi:[1,0]
	v_pk_add_f32 v[220:221], v[220:221], 1.0 op_sel_hi:[1,0]
	v_pk_add_f32 v[222:223], v[222:223], 1.0 op_sel_hi:[1,0]
	v_rcp_f32_e32 v216, v216
	v_rcp_f32_e32 v217, v217
	v_rcp_f32_e32 v218, v218
	v_rcp_f32_e32 v219, v219
	v_rcp_f32_e32 v220, v220
	v_rcp_f32_e32 v221, v221
	v_rcp_f32_e32 v222, v222
	v_rcp_f32_e32 v223, v223
	v_pk_mul_f32 v[134:135], v[134:135], v[216:217]
	v_pk_mul_f32 v[136:137], v[136:137], v[218:219]
	v_pk_mul_f32 v[130:131], v[130:131], v[220:221]
	v_pk_mul_f32 v[132:133], v[132:133], v[222:223]
	v_cvt_pk_bf16_f32 v184, v134, v135
	v_cvt_pk_bf16_f32 v185, v136, v137
	v_cvt_pk_bf16_f32 v186, v130, v131
	v_cvt_pk_bf16_f32 v187, v132, v133
	s_mov_b64 vcc, s[84:85]
	v_cndmask_b32_dpp v216, v184, v168, vcc quad_perm:[1,0,3,2] row_mask:0xf bank_mask:0xf
	v_cndmask_b32_dpp v217, v185, v169, vcc quad_perm:[1,0,3,2] row_mask:0xf bank_mask:0xf
	v_cndmask_b32_dpp v218, v186, v170, vcc quad_perm:[1,0,3,2] row_mask:0xf bank_mask:0xf
	v_cndmask_b32_dpp v219, v187, v171, vcc quad_perm:[1,0,3,2] row_mask:0xf bank_mask:0xf
	s_mov_b64 vcc, s[62:63]
	v_cndmask_b32_dpp v220, v168, v184, vcc quad_perm:[1,0,3,2] row_mask:0xf bank_mask:0xf
	v_cndmask_b32_dpp v221, v169, v185, vcc quad_perm:[1,0,3,2] row_mask:0xf bank_mask:0xf
	v_cndmask_b32_dpp v222, v170, v186, vcc quad_perm:[1,0,3,2] row_mask:0xf bank_mask:0xf
	v_cndmask_b32_dpp v223, v171, v187, vcc quad_perm:[1,0,3,2] row_mask:0xf bank_mask:0xf
	s_add_u32 s80, s10, 0x0
	s_addc_u32 s81, s11, 0
	s_add_u32 s82, s10, 0x2000
	s_addc_u32 s83, s11, 0
	global_store_dwordx4 v177, v[216:219], s[80:81]
	global_store_dwordx4 v177, v[220:223], s[82:83]
	v_pk_fma_f32 v[126:127], v[126:127], v[174:175], v[26:27] op_sel_hi:[1,0,1]
	v_pk_fma_f32 v[128:129], v[128:129], v[174:175], v[28:29] op_sel_hi:[1,0,1]
	v_pk_fma_f32 v[122:123], v[122:123], v[174:175], v[30:31] op_sel_hi:[1,0,1]
	v_pk_fma_f32 v[124:125], v[124:125], v[174:175], v[32:33] op_sel_hi:[1,0,1]
	v_pk_mul_f32 v[216:217], v[126:127], s[88:89] op_sel_hi:[1,0]
	v_pk_mul_f32 v[218:219], v[128:129], s[88:89] op_sel_hi:[1,0]
	v_pk_mul_f32 v[220:221], v[122:123], s[88:89] op_sel_hi:[1,0]
	v_pk_mul_f32 v[222:223], v[124:125], s[88:89] op_sel_hi:[1,0]
	v_exp_f32_e32 v216, v216
	v_exp_f32_e32 v217, v217
	v_exp_f32_e32 v218, v218
	v_exp_f32_e32 v219, v219
	v_exp_f32_e32 v220, v220
	v_exp_f32_e32 v221, v221
	v_exp_f32_e32 v222, v222
	v_exp_f32_e32 v223, v223
	v_pk_add_f32 v[216:217], v[216:217], 1.0 op_sel_hi:[1,0]
	v_pk_add_f32 v[218:219], v[218:219], 1.0 op_sel_hi:[1,0]
	v_pk_add_f32 v[220:221], v[220:221], 1.0 op_sel_hi:[1,0]
	v_pk_add_f32 v[222:223], v[222:223], 1.0 op_sel_hi:[1,0]
	v_rcp_f32_e32 v216, v216
	v_rcp_f32_e32 v217, v217
	v_rcp_f32_e32 v218, v218
	v_rcp_f32_e32 v219, v219
	v_rcp_f32_e32 v220, v220
	v_rcp_f32_e32 v221, v221
	v_rcp_f32_e32 v222, v222
	v_rcp_f32_e32 v223, v223
	v_pk_mul_f32 v[126:127], v[126:127], v[216:217]
	v_pk_mul_f32 v[128:129], v[128:129], v[218:219]
	v_pk_mul_f32 v[122:123], v[122:123], v[220:221]
	v_pk_mul_f32 v[124:125], v[124:125], v[222:223]
	v_cvt_pk_bf16_f32 v168, v126, v127
	v_cvt_pk_bf16_f32 v169, v128, v129
	v_cvt_pk_bf16_f32 v170, v122, v123
	v_cvt_pk_bf16_f32 v171, v124, v125
	v_pk_fma_f32 v[118:119], v[118:119], v[174:175], v[42:43] op_sel_hi:[1,0,1]
	v_pk_fma_f32 v[120:121], v[120:121], v[174:175], v[44:45] op_sel_hi:[1,0,1]
	v_pk_fma_f32 v[114:115], v[114:115], v[174:175], v[46:47] op_sel_hi:[1,0,1]
	v_pk_fma_f32 v[116:117], v[116:117], v[174:175], v[48:49] op_sel_hi:[1,0,1]
	v_pk_mul_f32 v[216:217], v[118:119], s[88:89] op_sel_hi:[1,0]
	v_pk_mul_f32 v[218:219], v[120:121], s[88:89] op_sel_hi:[1,0]
	v_pk_mul_f32 v[220:221], v[114:115], s[88:89] op_sel_hi:[1,0]
	v_pk_mul_f32 v[222:223], v[116:117], s[88:89] op_sel_hi:[1,0]
	v_exp_f32_e32 v216, v216
	v_exp_f32_e32 v217, v217
	v_exp_f32_e32 v218, v218
	v_exp_f32_e32 v219, v219
	v_exp_f32_e32 v220, v220
	v_exp_f32_e32 v221, v221
	v_exp_f32_e32 v222, v222
	v_exp_f32_e32 v223, v223
	v_pk_add_f32 v[216:217], v[216:217], 1.0 op_sel_hi:[1,0]
	v_pk_add_f32 v[218:219], v[218:219], 1.0 op_sel_hi:[1,0]
	v_pk_add_f32 v[220:221], v[220:221], 1.0 op_sel_hi:[1,0]
	v_pk_add_f32 v[222:223], v[222:223], 1.0 op_sel_hi:[1,0]
	v_rcp_f32_e32 v216, v216
	v_rcp_f32_e32 v217, v217
	v_rcp_f32_e32 v218, v218
	v_rcp_f32_e32 v219, v219
	v_rcp_f32_e32 v220, v220
	v_rcp_f32_e32 v221, v221
	v_rcp_f32_e32 v222, v222
	v_rcp_f32_e32 v223, v223
	v_pk_mul_f32 v[118:119], v[118:119], v[216:217]
	v_pk_mul_f32 v[120:121], v[120:121], v[218:219]
	v_pk_mul_f32 v[114:115], v[114:115], v[220:221]
	v_pk_mul_f32 v[116:117], v[116:117], v[222:223]
	v_cvt_pk_bf16_f32 v184, v118, v119
	v_cvt_pk_bf16_f32 v185, v120, v121
	v_cvt_pk_bf16_f32 v186, v114, v115
	v_cvt_pk_bf16_f32 v187, v116, v117
	s_mov_b64 vcc, s[84:85]
	v_cndmask_b32_dpp v216, v184, v168, vcc quad_perm:[1,0,3,2] row_mask:0xf bank_mask:0xf
	v_cndmask_b32_dpp v217, v185, v169, vcc quad_perm:[1,0,3,2] row_mask:0xf bank_mask:0xf
	v_cndmask_b32_dpp v218, v186, v170, vcc quad_perm:[1,0,3,2] row_mask:0xf bank_mask:0xf
	v_cndmask_b32_dpp v219, v187, v171, vcc quad_perm:[1,0,3,2] row_mask:0xf bank_mask:0xf
	s_mov_b64 vcc, s[62:63]
	v_cndmask_b32_dpp v220, v168, v184, vcc quad_perm:[1,0,3,2] row_mask:0xf bank_mask:0xf
	v_cndmask_b32_dpp v221, v169, v185, vcc quad_perm:[1,0,3,2] row_mask:0xf bank_mask:0xf
	v_cndmask_b32_dpp v222, v170, v186, vcc quad_perm:[1,0,3,2] row_mask:0xf bank_mask:0xf
	v_cndmask_b32_dpp v223, v171, v187, vcc quad_perm:[1,0,3,2] row_mask:0xf bank_mask:0xf
	s_add_u32 s80, s10, 0x20000
	s_addc_u32 s81, s11, 0
	s_add_u32 s82, s10, 0x22000
	s_addc_u32 s83, s11, 0
	global_store_dwordx4 v177, v[216:219], s[80:81]
	global_store_dwordx4 v177, v[220:223], s[82:83]
	v_pk_fma_f32 v[110:111], v[110:111], v[176:177], v[26:27] op_sel_hi:[1,0,1]
	v_pk_fma_f32 v[112:113], v[112:113], v[176:177], v[28:29] op_sel_hi:[1,0,1]
	v_pk_fma_f32 v[106:107], v[106:107], v[176:177], v[30:31] op_sel_hi:[1,0,1]
	v_pk_fma_f32 v[108:109], v[108:109], v[176:177], v[32:33] op_sel_hi:[1,0,1]
	v_pk_mul_f32 v[216:217], v[110:111], s[88:89] op_sel_hi:[1,0]
	v_pk_mul_f32 v[218:219], v[112:113], s[88:89] op_sel_hi:[1,0]
	v_pk_mul_f32 v[220:221], v[106:107], s[88:89] op_sel_hi:[1,0]
	v_pk_mul_f32 v[222:223], v[108:109], s[88:89] op_sel_hi:[1,0]
	v_exp_f32_e32 v216, v216
	v_exp_f32_e32 v217, v217
	v_exp_f32_e32 v218, v218
	v_exp_f32_e32 v219, v219
	v_exp_f32_e32 v220, v220
	v_exp_f32_e32 v221, v221
	v_exp_f32_e32 v222, v222
	v_exp_f32_e32 v223, v223
	v_pk_add_f32 v[216:217], v[216:217], 1.0 op_sel_hi:[1,0]
	v_pk_add_f32 v[218:219], v[218:219], 1.0 op_sel_hi:[1,0]
	v_pk_add_f32 v[220:221], v[220:221], 1.0 op_sel_hi:[1,0]
	v_pk_add_f32 v[222:223], v[222:223], 1.0 op_sel_hi:[1,0]
	v_rcp_f32_e32 v216, v216
	v_rcp_f32_e32 v217, v217
	v_rcp_f32_e32 v218, v218
	v_rcp_f32_e32 v219, v219
	v_rcp_f32_e32 v220, v220
	v_rcp_f32_e32 v221, v221
	v_rcp_f32_e32 v222, v222
	v_rcp_f32_e32 v223, v223
	v_pk_mul_f32 v[110:111], v[110:111], v[216:217]
	v_pk_mul_f32 v[112:113], v[112:113], v[218:219]
	v_pk_mul_f32 v[106:107], v[106:107], v[220:221]
	v_pk_mul_f32 v[108:109], v[108:109], v[222:223]
	v_cvt_pk_bf16_f32 v168, v110, v111
	v_cvt_pk_bf16_f32 v169, v112, v113
	v_cvt_pk_bf16_f32 v170, v106, v107
	v_cvt_pk_bf16_f32 v171, v108, v109
	v_pk_fma_f32 v[102:103], v[102:103], v[176:177], v[42:43] op_sel_hi:[1,0,1]
	v_pk_fma_f32 v[104:105], v[104:105], v[176:177], v[44:45] op_sel_hi:[1,0,1]
	v_pk_fma_f32 v[98:99], v[98:99], v[176:177], v[46:47] op_sel_hi:[1,0,1]
	v_pk_fma_f32 v[100:101], v[100:101], v[176:177], v[48:49] op_sel_hi:[1,0,1]
	v_pk_mul_f32 v[216:217], v[102:103], s[88:89] op_sel_hi:[1,0]
	v_pk_mul_f32 v[218:219], v[104:105], s[88:89] op_sel_hi:[1,0]
	v_pk_mul_f32 v[220:221], v[98:99], s[88:89] op_sel_hi:[1,0]
	v_pk_mul_f32 v[222:223], v[100:101], s[88:89] op_sel_hi:[1,0]
	v_exp_f32_e32 v216, v216
	v_exp_f32_e32 v217, v217
	v_exp_f32_e32 v218, v218
	v_exp_f32_e32 v219, v219
	v_exp_f32_e32 v220, v220
	v_exp_f32_e32 v221, v221
	v_exp_f32_e32 v222, v222
	v_exp_f32_e32 v223, v223
	v_pk_add_f32 v[216:217], v[216:217], 1.0 op_sel_hi:[1,0]
	v_pk_add_f32 v[218:219], v[218:219], 1.0 op_sel_hi:[1,0]
	v_pk_add_f32 v[220:221], v[220:221], 1.0 op_sel_hi:[1,0]
	v_pk_add_f32 v[222:223], v[222:223], 1.0 op_sel_hi:[1,0]
	v_rcp_f32_e32 v216, v216
	v_rcp_f32_e32 v217, v217
	v_rcp_f32_e32 v218, v218
	v_rcp_f32_e32 v219, v219
	v_rcp_f32_e32 v220, v220
	v_rcp_f32_e32 v221, v221
	v_rcp_f32_e32 v222, v222
	v_rcp_f32_e32 v223, v223
	v_pk_mul_f32 v[102:103], v[102:103], v[216:217]
	v_pk_mul_f32 v[104:105], v[104:105], v[218:219]
	v_pk_mul_f32 v[98:99], v[98:99], v[220:221]
	v_pk_mul_f32 v[100:101], v[100:101], v[222:223]
	v_cvt_pk_bf16_f32 v184, v102, v103
	v_cvt_pk_bf16_f32 v185, v104, v105
	v_cvt_pk_bf16_f32 v186, v98, v99
	v_cvt_pk_bf16_f32 v187, v100, v101
	s_mov_b64 vcc, s[84:85]
	v_cndmask_b32_dpp v216, v184, v168, vcc quad_perm:[1,0,3,2] row_mask:0xf bank_mask:0xf
	v_cndmask_b32_dpp v217, v185, v169, vcc quad_perm:[1,0,3,2] row_mask:0xf bank_mask:0xf
	v_cndmask_b32_dpp v218, v186, v170, vcc quad_perm:[1,0,3,2] row_mask:0xf bank_mask:0xf
	v_cndmask_b32_dpp v219, v187, v171, vcc quad_perm:[1,0,3,2] row_mask:0xf bank_mask:0xf
	s_mov_b64 vcc, s[62:63]
	v_cndmask_b32_dpp v220, v168, v184, vcc quad_perm:[1,0,3,2] row_mask:0xf bank_mask:0xf
	v_cndmask_b32_dpp v221, v169, v185, vcc quad_perm:[1,0,3,2] row_mask:0xf bank_mask:0xf
	v_cndmask_b32_dpp v222, v170, v186, vcc quad_perm:[1,0,3,2] row_mask:0xf bank_mask:0xf
	v_cndmask_b32_dpp v223, v171, v187, vcc quad_perm:[1,0,3,2] row_mask:0xf bank_mask:0xf
	s_add_u32 s80, s10, 0x40000
	s_addc_u32 s81, s11, 0
	s_add_u32 s82, s10, 0x42000
	s_addc_u32 s83, s11, 0
	global_store_dwordx4 v177, v[216:219], s[80:81]
	global_store_dwordx4 v177, v[220:223], s[82:83]
	v_pk_fma_f32 v[94:95], v[94:95], v[178:179], v[26:27] op_sel_hi:[1,0,1]
	v_pk_fma_f32 v[96:97], v[96:97], v[178:179], v[28:29] op_sel_hi:[1,0,1]
	v_pk_fma_f32 v[90:91], v[90:91], v[178:179], v[30:31] op_sel_hi:[1,0,1]
	v_pk_fma_f32 v[92:93], v[92:93], v[178:179], v[32:33] op_sel_hi:[1,0,1]
	v_pk_mul_f32 v[216:217], v[94:95], s[88:89] op_sel_hi:[1,0]
	v_pk_mul_f32 v[218:219], v[96:97], s[88:89] op_sel_hi:[1,0]
	v_pk_mul_f32 v[220:221], v[90:91], s[88:89] op_sel_hi:[1,0]
	v_pk_mul_f32 v[222:223], v[92:93], s[88:89] op_sel_hi:[1,0]
	v_exp_f32_e32 v216, v216
	v_exp_f32_e32 v217, v217
	v_exp_f32_e32 v218, v218
	v_exp_f32_e32 v219, v219
	v_exp_f32_e32 v220, v220
	v_exp_f32_e32 v221, v221
	v_exp_f32_e32 v222, v222
	v_exp_f32_e32 v223, v223
	v_pk_add_f32 v[216:217], v[216:217], 1.0 op_sel_hi:[1,0]
	v_pk_add_f32 v[218:219], v[218:219], 1.0 op_sel_hi:[1,0]
	v_pk_add_f32 v[220:221], v[220:221], 1.0 op_sel_hi:[1,0]
	v_pk_add_f32 v[222:223], v[222:223], 1.0 op_sel_hi:[1,0]
	v_rcp_f32_e32 v216, v216
	v_rcp_f32_e32 v217, v217
	v_rcp_f32_e32 v218, v218
	v_rcp_f32_e32 v219, v219
	v_rcp_f32_e32 v220, v220
	v_rcp_f32_e32 v221, v221
	v_rcp_f32_e32 v222, v222
	v_rcp_f32_e32 v223, v223
	v_pk_mul_f32 v[94:95], v[94:95], v[216:217]
	v_pk_mul_f32 v[96:97], v[96:97], v[218:219]
	v_pk_mul_f32 v[90:91], v[90:91], v[220:221]
	v_pk_mul_f32 v[92:93], v[92:93], v[222:223]
	v_cvt_pk_bf16_f32 v168, v94, v95
	v_cvt_pk_bf16_f32 v169, v96, v97
	v_cvt_pk_bf16_f32 v170, v90, v91
	v_cvt_pk_bf16_f32 v171, v92, v93
	v_pk_fma_f32 v[86:87], v[86:87], v[178:179], v[42:43] op_sel_hi:[1,0,1]
	v_pk_fma_f32 v[88:89], v[88:89], v[178:179], v[44:45] op_sel_hi:[1,0,1]
	v_pk_fma_f32 v[82:83], v[82:83], v[178:179], v[46:47] op_sel_hi:[1,0,1]
	v_pk_fma_f32 v[84:85], v[84:85], v[178:179], v[48:49] op_sel_hi:[1,0,1]
	v_pk_mul_f32 v[216:217], v[86:87], s[88:89] op_sel_hi:[1,0]
	v_pk_mul_f32 v[218:219], v[88:89], s[88:89] op_sel_hi:[1,0]
	v_pk_mul_f32 v[220:221], v[82:83], s[88:89] op_sel_hi:[1,0]
	v_pk_mul_f32 v[222:223], v[84:85], s[88:89] op_sel_hi:[1,0]
	v_exp_f32_e32 v216, v216
	v_exp_f32_e32 v217, v217
	v_exp_f32_e32 v218, v218
	v_exp_f32_e32 v219, v219
	v_exp_f32_e32 v220, v220
	v_exp_f32_e32 v221, v221
	v_exp_f32_e32 v222, v222
	v_exp_f32_e32 v223, v223
	v_pk_add_f32 v[216:217], v[216:217], 1.0 op_sel_hi:[1,0]
	v_pk_add_f32 v[218:219], v[218:219], 1.0 op_sel_hi:[1,0]
	v_pk_add_f32 v[220:221], v[220:221], 1.0 op_sel_hi:[1,0]
	v_pk_add_f32 v[222:223], v[222:223], 1.0 op_sel_hi:[1,0]
	v_rcp_f32_e32 v216, v216
	v_rcp_f32_e32 v217, v217
	v_rcp_f32_e32 v218, v218
	v_rcp_f32_e32 v219, v219
	v_rcp_f32_e32 v220, v220
	v_rcp_f32_e32 v221, v221
	v_rcp_f32_e32 v222, v222
	v_rcp_f32_e32 v223, v223
	v_pk_mul_f32 v[86:87], v[86:87], v[216:217]
	v_pk_mul_f32 v[88:89], v[88:89], v[218:219]
	v_pk_mul_f32 v[82:83], v[82:83], v[220:221]
	v_pk_mul_f32 v[84:85], v[84:85], v[222:223]
	v_cvt_pk_bf16_f32 v184, v86, v87
	v_cvt_pk_bf16_f32 v185, v88, v89
	v_cvt_pk_bf16_f32 v186, v82, v83
	v_cvt_pk_bf16_f32 v187, v84, v85
	s_mov_b64 vcc, s[84:85]
	v_cndmask_b32_dpp v216, v184, v168, vcc quad_perm:[1,0,3,2] row_mask:0xf bank_mask:0xf
	v_cndmask_b32_dpp v217, v185, v169, vcc quad_perm:[1,0,3,2] row_mask:0xf bank_mask:0xf
	v_cndmask_b32_dpp v218, v186, v170, vcc quad_perm:[1,0,3,2] row_mask:0xf bank_mask:0xf
	v_cndmask_b32_dpp v219, v187, v171, vcc quad_perm:[1,0,3,2] row_mask:0xf bank_mask:0xf
	s_mov_b64 vcc, s[62:63]
	v_cndmask_b32_dpp v220, v168, v184, vcc quad_perm:[1,0,3,2] row_mask:0xf bank_mask:0xf
	v_cndmask_b32_dpp v221, v169, v185, vcc quad_perm:[1,0,3,2] row_mask:0xf bank_mask:0xf
	v_cndmask_b32_dpp v222, v170, v186, vcc quad_perm:[1,0,3,2] row_mask:0xf bank_mask:0xf
	v_cndmask_b32_dpp v223, v171, v187, vcc quad_perm:[1,0,3,2] row_mask:0xf bank_mask:0xf
	s_add_u32 s80, s10, 0x60000
	s_addc_u32 s81, s11, 0
	s_add_u32 s82, s10, 0x62000
	s_addc_u32 s83, s11, 0
	global_store_dwordx4 v177, v[216:219], s[80:81]
	global_store_dwordx4 v177, v[220:223], s[82:83]
	v_pk_fma_f32 v[78:79], v[78:79], v[180:181], v[26:27] op_sel_hi:[1,0,1]
	v_pk_fma_f32 v[80:81], v[80:81], v[180:181], v[28:29] op_sel_hi:[1,0,1]
	v_pk_fma_f32 v[74:75], v[74:75], v[180:181], v[30:31] op_sel_hi:[1,0,1]
	v_pk_fma_f32 v[76:77], v[76:77], v[180:181], v[32:33] op_sel_hi:[1,0,1]
	v_pk_mul_f32 v[216:217], v[78:79], s[88:89] op_sel_hi:[1,0]
	v_pk_mul_f32 v[218:219], v[80:81], s[88:89] op_sel_hi:[1,0]
	v_pk_mul_f32 v[220:221], v[74:75], s[88:89] op_sel_hi:[1,0]
	v_pk_mul_f32 v[222:223], v[76:77], s[88:89] op_sel_hi:[1,0]
	v_exp_f32_e32 v216, v216
	v_exp_f32_e32 v217, v217
	v_exp_f32_e32 v218, v218
	v_exp_f32_e32 v219, v219
	v_exp_f32_e32 v220, v220
	v_exp_f32_e32 v221, v221
	v_exp_f32_e32 v222, v222
	v_exp_f32_e32 v223, v223
	v_pk_add_f32 v[216:217], v[216:217], 1.0 op_sel_hi:[1,0]
	v_pk_add_f32 v[218:219], v[218:219], 1.0 op_sel_hi:[1,0]
	v_pk_add_f32 v[220:221], v[220:221], 1.0 op_sel_hi:[1,0]
	v_pk_add_f32 v[222:223], v[222:223], 1.0 op_sel_hi:[1,0]
	v_rcp_f32_e32 v216, v216
	v_rcp_f32_e32 v217, v217
	v_rcp_f32_e32 v218, v218
	v_rcp_f32_e32 v219, v219
	v_rcp_f32_e32 v220, v220
	v_rcp_f32_e32 v221, v221
	v_rcp_f32_e32 v222, v222
	v_rcp_f32_e32 v223, v223
	v_pk_mul_f32 v[78:79], v[78:79], v[216:217]
	v_pk_mul_f32 v[80:81], v[80:81], v[218:219]
	v_pk_mul_f32 v[74:75], v[74:75], v[220:221]
	v_pk_mul_f32 v[76:77], v[76:77], v[222:223]
	v_cvt_pk_bf16_f32 v168, v78, v79
	v_cvt_pk_bf16_f32 v169, v80, v81
	v_cvt_pk_bf16_f32 v170, v74, v75
	v_cvt_pk_bf16_f32 v171, v76, v77
	v_pk_fma_f32 v[70:71], v[70:71], v[180:181], v[42:43] op_sel_hi:[1,0,1]
	v_pk_fma_f32 v[72:73], v[72:73], v[180:181], v[44:45] op_sel_hi:[1,0,1]
	v_pk_fma_f32 v[66:67], v[66:67], v[180:181], v[46:47] op_sel_hi:[1,0,1]
	v_pk_fma_f32 v[68:69], v[68:69], v[180:181], v[48:49] op_sel_hi:[1,0,1]
	v_pk_mul_f32 v[216:217], v[70:71], s[88:89] op_sel_hi:[1,0]
	v_pk_mul_f32 v[218:219], v[72:73], s[88:89] op_sel_hi:[1,0]
	v_pk_mul_f32 v[220:221], v[66:67], s[88:89] op_sel_hi:[1,0]
	v_pk_mul_f32 v[222:223], v[68:69], s[88:89] op_sel_hi:[1,0]
	v_exp_f32_e32 v216, v216
	v_exp_f32_e32 v217, v217
	v_exp_f32_e32 v218, v218
	v_exp_f32_e32 v219, v219
	v_exp_f32_e32 v220, v220
	v_exp_f32_e32 v221, v221
	v_exp_f32_e32 v222, v222
	v_exp_f32_e32 v223, v223
	v_pk_add_f32 v[216:217], v[216:217], 1.0 op_sel_hi:[1,0]
	v_pk_add_f32 v[218:219], v[218:219], 1.0 op_sel_hi:[1,0]
	v_pk_add_f32 v[220:221], v[220:221], 1.0 op_sel_hi:[1,0]
	v_pk_add_f32 v[222:223], v[222:223], 1.0 op_sel_hi:[1,0]
	v_rcp_f32_e32 v216, v216
	v_rcp_f32_e32 v217, v217
	v_rcp_f32_e32 v218, v218
	v_rcp_f32_e32 v219, v219
	v_rcp_f32_e32 v220, v220
	v_rcp_f32_e32 v221, v221
	v_rcp_f32_e32 v222, v222
	v_rcp_f32_e32 v223, v223
	v_pk_mul_f32 v[70:71], v[70:71], v[216:217]
	v_pk_mul_f32 v[72:73], v[72:73], v[218:219]
	v_pk_mul_f32 v[66:67], v[66:67], v[220:221]
	v_pk_mul_f32 v[68:69], v[68:69], v[222:223]
	v_cvt_pk_bf16_f32 v184, v70, v71
	v_cvt_pk_bf16_f32 v185, v72, v73
	v_cvt_pk_bf16_f32 v186, v66, v67
	v_cvt_pk_bf16_f32 v187, v68, v69
	s_mov_b64 vcc, s[84:85]
	v_cndmask_b32_dpp v216, v184, v168, vcc quad_perm:[1,0,3,2] row_mask:0xf bank_mask:0xf
	v_cndmask_b32_dpp v217, v185, v169, vcc quad_perm:[1,0,3,2] row_mask:0xf bank_mask:0xf
	v_cndmask_b32_dpp v218, v186, v170, vcc quad_perm:[1,0,3,2] row_mask:0xf bank_mask:0xf
	v_cndmask_b32_dpp v219, v187, v171, vcc quad_perm:[1,0,3,2] row_mask:0xf bank_mask:0xf
	s_mov_b64 vcc, s[62:63]
	v_cndmask_b32_dpp v220, v168, v184, vcc quad_perm:[1,0,3,2] row_mask:0xf bank_mask:0xf
	v_cndmask_b32_dpp v221, v169, v185, vcc quad_perm:[1,0,3,2] row_mask:0xf bank_mask:0xf
	v_cndmask_b32_dpp v222, v170, v186, vcc quad_perm:[1,0,3,2] row_mask:0xf bank_mask:0xf
	v_cndmask_b32_dpp v223, v171, v187, vcc quad_perm:[1,0,3,2] row_mask:0xf bank_mask:0xf
	s_add_u32 s80, s10, 0x100000
	s_addc_u32 s81, s11, 0
	s_add_u32 s82, s10, 0x102000
	s_addc_u32 s83, s11, 0
	global_store_dwordx4 v177, v[216:219], s[80:81]
	global_store_dwordx4 v177, v[220:223], s[82:83]
	v_pk_fma_f32 v[62:63], v[62:63], v[182:183], v[26:27] op_sel_hi:[1,0,1]
	v_pk_fma_f32 v[64:65], v[64:65], v[182:183], v[28:29] op_sel_hi:[1,0,1]
	v_pk_fma_f32 v[58:59], v[58:59], v[182:183], v[30:31] op_sel_hi:[1,0,1]
	v_pk_fma_f32 v[60:61], v[60:61], v[182:183], v[32:33] op_sel_hi:[1,0,1]
	v_pk_mul_f32 v[216:217], v[62:63], s[88:89] op_sel_hi:[1,0]
	v_pk_mul_f32 v[218:219], v[64:65], s[88:89] op_sel_hi:[1,0]
	v_pk_mul_f32 v[220:221], v[58:59], s[88:89] op_sel_hi:[1,0]
	v_pk_mul_f32 v[222:223], v[60:61], s[88:89] op_sel_hi:[1,0]
	v_exp_f32_e32 v216, v216
	v_exp_f32_e32 v217, v217
	v_exp_f32_e32 v218, v218
	v_exp_f32_e32 v219, v219
	v_exp_f32_e32 v220, v220
	v_exp_f32_e32 v221, v221
	v_exp_f32_e32 v222, v222
	v_exp_f32_e32 v223, v223
	v_pk_add_f32 v[216:217], v[216:217], 1.0 op_sel_hi:[1,0]
	v_pk_add_f32 v[218:219], v[218:219], 1.0 op_sel_hi:[1,0]
	v_pk_add_f32 v[220:221], v[220:221], 1.0 op_sel_hi:[1,0]
	v_pk_add_f32 v[222:223], v[222:223], 1.0 op_sel_hi:[1,0]
	v_rcp_f32_e32 v216, v216
	v_rcp_f32_e32 v217, v217
	v_rcp_f32_e32 v218, v218
	v_rcp_f32_e32 v219, v219
	v_rcp_f32_e32 v220, v220
	v_rcp_f32_e32 v221, v221
	v_rcp_f32_e32 v222, v222
	v_rcp_f32_e32 v223, v223
	v_pk_mul_f32 v[62:63], v[62:63], v[216:217]
	v_pk_mul_f32 v[64:65], v[64:65], v[218:219]
	v_pk_mul_f32 v[58:59], v[58:59], v[220:221]
	v_pk_mul_f32 v[60:61], v[60:61], v[222:223]
	v_cvt_pk_bf16_f32 v168, v62, v63
	v_cvt_pk_bf16_f32 v169, v64, v65
	v_cvt_pk_bf16_f32 v170, v58, v59
	v_cvt_pk_bf16_f32 v171, v60, v61
	v_pk_fma_f32 v[54:55], v[54:55], v[182:183], v[42:43] op_sel_hi:[1,0,1]
	v_pk_fma_f32 v[56:57], v[56:57], v[182:183], v[44:45] op_sel_hi:[1,0,1]
	v_pk_fma_f32 v[50:51], v[50:51], v[182:183], v[46:47] op_sel_hi:[1,0,1]
	v_pk_fma_f32 v[52:53], v[52:53], v[182:183], v[48:49] op_sel_hi:[1,0,1]
	v_pk_mul_f32 v[216:217], v[54:55], s[88:89] op_sel_hi:[1,0]
	v_pk_mul_f32 v[218:219], v[56:57], s[88:89] op_sel_hi:[1,0]
	v_pk_mul_f32 v[220:221], v[50:51], s[88:89] op_sel_hi:[1,0]
	v_pk_mul_f32 v[222:223], v[52:53], s[88:89] op_sel_hi:[1,0]
	v_exp_f32_e32 v216, v216
	v_exp_f32_e32 v217, v217
	v_exp_f32_e32 v218, v218
	v_exp_f32_e32 v219, v219
	v_exp_f32_e32 v220, v220
	v_exp_f32_e32 v221, v221
	v_exp_f32_e32 v222, v222
	v_exp_f32_e32 v223, v223
	v_pk_add_f32 v[216:217], v[216:217], 1.0 op_sel_hi:[1,0]
	v_pk_add_f32 v[218:219], v[218:219], 1.0 op_sel_hi:[1,0]
	v_pk_add_f32 v[220:221], v[220:221], 1.0 op_sel_hi:[1,0]
	v_pk_add_f32 v[222:223], v[222:223], 1.0 op_sel_hi:[1,0]
	v_rcp_f32_e32 v216, v216
	v_rcp_f32_e32 v217, v217
	v_rcp_f32_e32 v218, v218
	v_rcp_f32_e32 v219, v219
	v_rcp_f32_e32 v220, v220
	v_rcp_f32_e32 v221, v221
	v_rcp_f32_e32 v222, v222
	v_rcp_f32_e32 v223, v223
	v_pk_mul_f32 v[54:55], v[54:55], v[216:217]
	v_pk_mul_f32 v[56:57], v[56:57], v[218:219]
	v_pk_mul_f32 v[50:51], v[50:51], v[220:221]
	v_pk_mul_f32 v[52:53], v[52:53], v[222:223]
	v_cvt_pk_bf16_f32 v184, v54, v55
	v_cvt_pk_bf16_f32 v185, v56, v57
	v_cvt_pk_bf16_f32 v186, v50, v51
	v_cvt_pk_bf16_f32 v187, v52, v53
	s_mov_b64 vcc, s[84:85]
	v_cndmask_b32_dpp v216, v184, v168, vcc quad_perm:[1,0,3,2] row_mask:0xf bank_mask:0xf
	v_cndmask_b32_dpp v217, v185, v169, vcc quad_perm:[1,0,3,2] row_mask:0xf bank_mask:0xf
	v_cndmask_b32_dpp v218, v186, v170, vcc quad_perm:[1,0,3,2] row_mask:0xf bank_mask:0xf
	v_cndmask_b32_dpp v219, v187, v171, vcc quad_perm:[1,0,3,2] row_mask:0xf bank_mask:0xf
	s_mov_b64 vcc, s[62:63]
	v_cndmask_b32_dpp v220, v168, v184, vcc quad_perm:[1,0,3,2] row_mask:0xf bank_mask:0xf
	v_cndmask_b32_dpp v221, v169, v185, vcc quad_perm:[1,0,3,2] row_mask:0xf bank_mask:0xf
	v_cndmask_b32_dpp v222, v170, v186, vcc quad_perm:[1,0,3,2] row_mask:0xf bank_mask:0xf
	v_cndmask_b32_dpp v223, v171, v187, vcc quad_perm:[1,0,3,2] row_mask:0xf bank_mask:0xf
	s_add_u32 s80, s10, 0x120000
	s_addc_u32 s81, s11, 0
	s_add_u32 s82, s10, 0x122000
	s_addc_u32 s83, s11, 0
	global_store_dwordx4 v177, v[216:219], s[80:81]
	global_store_dwordx4 v177, v[220:223], s[82:83]
	v_pk_fma_f32 v[38:39], v[38:39], v[188:189], v[26:27] op_sel_hi:[1,0,1]
	v_pk_fma_f32 v[40:41], v[40:41], v[188:189], v[28:29] op_sel_hi:[1,0,1]
	v_pk_fma_f32 v[34:35], v[34:35], v[188:189], v[30:31] op_sel_hi:[1,0,1]
	v_pk_fma_f32 v[36:37], v[36:37], v[188:189], v[32:33] op_sel_hi:[1,0,1]
	v_pk_mul_f32 v[216:217], v[38:39], s[88:89] op_sel_hi:[1,0]
	v_pk_mul_f32 v[218:219], v[40:41], s[88:89] op_sel_hi:[1,0]
	v_pk_mul_f32 v[220:221], v[34:35], s[88:89] op_sel_hi:[1,0]
	v_pk_mul_f32 v[222:223], v[36:37], s[88:89] op_sel_hi:[1,0]
	v_exp_f32_e32 v216, v216
	v_exp_f32_e32 v217, v217
	v_exp_f32_e32 v218, v218
	v_exp_f32_e32 v219, v219
	v_exp_f32_e32 v220, v220
	v_exp_f32_e32 v221, v221
	v_exp_f32_e32 v222, v222
	v_exp_f32_e32 v223, v223
	v_pk_add_f32 v[216:217], v[216:217], 1.0 op_sel_hi:[1,0]
	v_pk_add_f32 v[218:219], v[218:219], 1.0 op_sel_hi:[1,0]
	v_pk_add_f32 v[220:221], v[220:221], 1.0 op_sel_hi:[1,0]
	v_pk_add_f32 v[222:223], v[222:223], 1.0 op_sel_hi:[1,0]
	v_rcp_f32_e32 v216, v216
	v_rcp_f32_e32 v217, v217
	v_rcp_f32_e32 v218, v218
	v_rcp_f32_e32 v219, v219
	v_rcp_f32_e32 v220, v220
	v_rcp_f32_e32 v221, v221
	v_rcp_f32_e32 v222, v222
	v_rcp_f32_e32 v223, v223
	v_pk_mul_f32 v[38:39], v[38:39], v[216:217]
	v_pk_mul_f32 v[40:41], v[40:41], v[218:219]
	v_pk_mul_f32 v[34:35], v[34:35], v[220:221]
	v_pk_mul_f32 v[36:37], v[36:37], v[222:223]
	v_cvt_pk_bf16_f32 v168, v38, v39
	v_cvt_pk_bf16_f32 v169, v40, v41
	v_cvt_pk_bf16_f32 v170, v34, v35
	v_cvt_pk_bf16_f32 v171, v36, v37
	v_pk_fma_f32 v[22:23], v[22:23], v[188:189], v[42:43] op_sel_hi:[1,0,1]
	v_pk_fma_f32 v[24:25], v[24:25], v[188:189], v[44:45] op_sel_hi:[1,0,1]
	v_pk_fma_f32 v[18:19], v[18:19], v[188:189], v[46:47] op_sel_hi:[1,0,1]
	v_pk_fma_f32 v[20:21], v[20:21], v[188:189], v[48:49] op_sel_hi:[1,0,1]
	v_pk_mul_f32 v[216:217], v[22:23], s[88:89] op_sel_hi:[1,0]
	v_pk_mul_f32 v[218:219], v[24:25], s[88:89] op_sel_hi:[1,0]
	v_pk_mul_f32 v[220:221], v[18:19], s[88:89] op_sel_hi:[1,0]
	v_pk_mul_f32 v[222:223], v[20:21], s[88:89] op_sel_hi:[1,0]
	v_exp_f32_e32 v216, v216
	v_exp_f32_e32 v217, v217
	v_exp_f32_e32 v218, v218
	v_exp_f32_e32 v219, v219
	v_exp_f32_e32 v220, v220
	v_exp_f32_e32 v221, v221
	v_exp_f32_e32 v222, v222
	v_exp_f32_e32 v223, v223
	v_pk_add_f32 v[216:217], v[216:217], 1.0 op_sel_hi:[1,0]
	v_pk_add_f32 v[218:219], v[218:219], 1.0 op_sel_hi:[1,0]
	v_pk_add_f32 v[220:221], v[220:221], 1.0 op_sel_hi:[1,0]
	v_pk_add_f32 v[222:223], v[222:223], 1.0 op_sel_hi:[1,0]
	v_rcp_f32_e32 v216, v216
	v_rcp_f32_e32 v217, v217
	v_rcp_f32_e32 v218, v218
	v_rcp_f32_e32 v219, v219
	v_rcp_f32_e32 v220, v220
	v_rcp_f32_e32 v221, v221
	v_rcp_f32_e32 v222, v222
	v_rcp_f32_e32 v223, v223
	v_pk_mul_f32 v[22:23], v[22:23], v[216:217]
	v_pk_mul_f32 v[24:25], v[24:25], v[218:219]
	v_pk_mul_f32 v[18:19], v[18:19], v[220:221]
	v_pk_mul_f32 v[20:21], v[20:21], v[222:223]
	v_cvt_pk_bf16_f32 v184, v22, v23
	v_cvt_pk_bf16_f32 v185, v24, v25
	v_cvt_pk_bf16_f32 v186, v18, v19
	v_cvt_pk_bf16_f32 v187, v20, v21
	s_mov_b64 vcc, s[84:85]
	v_cndmask_b32_dpp v216, v184, v168, vcc quad_perm:[1,0,3,2] row_mask:0xf bank_mask:0xf
	v_cndmask_b32_dpp v217, v185, v169, vcc quad_perm:[1,0,3,2] row_mask:0xf bank_mask:0xf
	v_cndmask_b32_dpp v218, v186, v170, vcc quad_perm:[1,0,3,2] row_mask:0xf bank_mask:0xf
	v_cndmask_b32_dpp v219, v187, v171, vcc quad_perm:[1,0,3,2] row_mask:0xf bank_mask:0xf
	s_mov_b64 vcc, s[62:63]
	v_cndmask_b32_dpp v220, v168, v184, vcc quad_perm:[1,0,3,2] row_mask:0xf bank_mask:0xf
	v_cndmask_b32_dpp v221, v169, v185, vcc quad_perm:[1,0,3,2] row_mask:0xf bank_mask:0xf
	v_cndmask_b32_dpp v222, v170, v186, vcc quad_perm:[1,0,3,2] row_mask:0xf bank_mask:0xf
	v_cndmask_b32_dpp v223, v171, v187, vcc quad_perm:[1,0,3,2] row_mask:0xf bank_mask:0xf
	s_add_u32 s80, s10, 0x140000
	s_addc_u32 s81, s11, 0
	s_add_u32 s82, s10, 0x142000
	s_addc_u32 s83, s11, 0
	global_store_dwordx4 v177, v[216:219], s[80:81]
	global_store_dwordx4 v177, v[220:223], s[82:83]
	v_pk_fma_f32 v[14:15], v[14:15], v[240:241], v[26:27] op_sel_hi:[1,0,1]
	v_pk_fma_f32 v[16:17], v[16:17], v[240:241], v[28:29] op_sel_hi:[1,0,1]
	v_pk_fma_f32 v[10:11], v[10:11], v[240:241], v[30:31] op_sel_hi:[1,0,1]
	v_pk_fma_f32 v[12:13], v[12:13], v[240:241], v[32:33] op_sel_hi:[1,0,1]
	v_pk_mul_f32 v[216:217], v[14:15], s[88:89] op_sel_hi:[1,0]
	v_pk_mul_f32 v[218:219], v[16:17], s[88:89] op_sel_hi:[1,0]
	v_pk_mul_f32 v[220:221], v[10:11], s[88:89] op_sel_hi:[1,0]
	v_pk_mul_f32 v[222:223], v[12:13], s[88:89] op_sel_hi:[1,0]
	v_exp_f32_e32 v216, v216
	v_exp_f32_e32 v217, v217
	v_exp_f32_e32 v218, v218
	v_exp_f32_e32 v219, v219
	v_exp_f32_e32 v220, v220
	v_exp_f32_e32 v221, v221
	v_exp_f32_e32 v222, v222
	v_exp_f32_e32 v223, v223
	v_pk_add_f32 v[216:217], v[216:217], 1.0 op_sel_hi:[1,0]
	v_pk_add_f32 v[218:219], v[218:219], 1.0 op_sel_hi:[1,0]
	v_pk_add_f32 v[220:221], v[220:221], 1.0 op_sel_hi:[1,0]
	v_pk_add_f32 v[222:223], v[222:223], 1.0 op_sel_hi:[1,0]
	v_rcp_f32_e32 v216, v216
	v_rcp_f32_e32 v217, v217
	v_rcp_f32_e32 v218, v218
	v_rcp_f32_e32 v219, v219
	v_rcp_f32_e32 v220, v220
	v_rcp_f32_e32 v221, v221
	v_rcp_f32_e32 v222, v222
	v_rcp_f32_e32 v223, v223
	v_pk_mul_f32 v[14:15], v[14:15], v[216:217]
	v_pk_mul_f32 v[16:17], v[16:17], v[218:219]
	v_pk_mul_f32 v[10:11], v[10:11], v[220:221]
	v_pk_mul_f32 v[12:13], v[12:13], v[222:223]
	v_cvt_pk_bf16_f32 v168, v14, v15
	v_cvt_pk_bf16_f32 v169, v16, v17
	v_cvt_pk_bf16_f32 v170, v10, v11
	v_cvt_pk_bf16_f32 v171, v12, v13
	v_pk_fma_f32 v[6:7], v[6:7], v[240:241], v[42:43] op_sel_hi:[1,0,1]
	v_pk_fma_f32 v[8:9], v[8:9], v[240:241], v[44:45] op_sel_hi:[1,0,1]
	v_pk_fma_f32 v[2:3], v[2:3], v[240:241], v[46:47] op_sel_hi:[1,0,1]
	v_pk_fma_f32 v[4:5], v[4:5], v[240:241], v[48:49] op_sel_hi:[1,0,1]
	v_pk_mul_f32 v[216:217], v[6:7], s[88:89] op_sel_hi:[1,0]
	v_pk_mul_f32 v[218:219], v[8:9], s[88:89] op_sel_hi:[1,0]
	v_pk_mul_f32 v[220:221], v[2:3], s[88:89] op_sel_hi:[1,0]
	v_pk_mul_f32 v[222:223], v[4:5], s[88:89] op_sel_hi:[1,0]
	v_exp_f32_e32 v216, v216
	v_exp_f32_e32 v217, v217
	v_exp_f32_e32 v218, v218
	v_exp_f32_e32 v219, v219
	v_exp_f32_e32 v220, v220
	v_exp_f32_e32 v221, v221
	v_exp_f32_e32 v222, v222
	v_exp_f32_e32 v223, v223
	v_pk_add_f32 v[216:217], v[216:217], 1.0 op_sel_hi:[1,0]
	v_pk_add_f32 v[218:219], v[218:219], 1.0 op_sel_hi:[1,0]
	v_pk_add_f32 v[220:221], v[220:221], 1.0 op_sel_hi:[1,0]
	v_pk_add_f32 v[222:223], v[222:223], 1.0 op_sel_hi:[1,0]
	v_rcp_f32_e32 v216, v216
	v_rcp_f32_e32 v217, v217
	v_rcp_f32_e32 v218, v218
	v_rcp_f32_e32 v219, v219
	v_rcp_f32_e32 v220, v220
	v_rcp_f32_e32 v221, v221
	v_rcp_f32_e32 v222, v222
	v_rcp_f32_e32 v223, v223
	v_pk_mul_f32 v[6:7], v[6:7], v[216:217]
	v_pk_mul_f32 v[8:9], v[8:9], v[218:219]
	v_pk_mul_f32 v[2:3], v[2:3], v[220:221]
	v_pk_mul_f32 v[4:5], v[4:5], v[222:223]
	v_cvt_pk_bf16_f32 v184, v6, v7
	v_cvt_pk_bf16_f32 v185, v8, v9
	v_cvt_pk_bf16_f32 v186, v2, v3
	v_cvt_pk_bf16_f32 v187, v4, v5
	s_mov_b64 vcc, s[84:85]
	v_cndmask_b32_dpp v216, v184, v168, vcc quad_perm:[1,0,3,2] row_mask:0xf bank_mask:0xf
	v_cndmask_b32_dpp v217, v185, v169, vcc quad_perm:[1,0,3,2] row_mask:0xf bank_mask:0xf
	v_cndmask_b32_dpp v218, v186, v170, vcc quad_perm:[1,0,3,2] row_mask:0xf bank_mask:0xf
	v_cndmask_b32_dpp v219, v187, v171, vcc quad_perm:[1,0,3,2] row_mask:0xf bank_mask:0xf
	s_mov_b64 vcc, s[62:63]
	v_cndmask_b32_dpp v220, v168, v184, vcc quad_perm:[1,0,3,2] row_mask:0xf bank_mask:0xf
	v_cndmask_b32_dpp v221, v169, v185, vcc quad_perm:[1,0,3,2] row_mask:0xf bank_mask:0xf
	v_cndmask_b32_dpp v222, v170, v186, vcc quad_perm:[1,0,3,2] row_mask:0xf bank_mask:0xf
	v_cndmask_b32_dpp v223, v171, v187, vcc quad_perm:[1,0,3,2] row_mask:0xf bank_mask:0xf
	s_add_u32 s80, s10, 0x160000
	s_addc_u32 s81, s11, 0
	s_add_u32 s82, s10, 0x162000
	s_addc_u32 s83, s11, 0
	global_store_dwordx4 v177, v[216:219], s[80:81]
	global_store_dwordx4 v177, v[220:223], s[82:83]
	s_branch .Lact1_hgin_done
.Lact1_hgin_id:
	s_waitcnt lgkmcnt(0)
	v_pk_fma_f32 v[142:143], v[142:143], v[172:173], v[26:27] op_sel_hi:[1,0,1]
	v_pk_fma_f32 v[144:145], v[144:145], v[172:173], v[28:29] op_sel_hi:[1,0,1]
	v_pk_fma_f32 v[138:139], v[138:139], v[172:173], v[30:31] op_sel_hi:[1,0,1]
	v_pk_fma_f32 v[140:141], v[140:141], v[172:173], v[32:33] op_sel_hi:[1,0,1]
	v_cvt_pk_bf16_f32 v168, v142, v143
	v_cvt_pk_bf16_f32 v169, v144, v145
	v_cvt_pk_bf16_f32 v170, v138, v139
	v_cvt_pk_bf16_f32 v171, v140, v141
	v_pk_fma_f32 v[134:135], v[134:135], v[172:173], v[42:43] op_sel_hi:[1,0,1]
	v_pk_fma_f32 v[136:137], v[136:137], v[172:173], v[44:45] op_sel_hi:[1,0,1]
	v_pk_fma_f32 v[130:131], v[130:131], v[172:173], v[46:47] op_sel_hi:[1,0,1]
	v_pk_fma_f32 v[132:133], v[132:133], v[172:173], v[48:49] op_sel_hi:[1,0,1]
	v_cvt_pk_bf16_f32 v184, v134, v135
	v_cvt_pk_bf16_f32 v185, v136, v137
	v_cvt_pk_bf16_f32 v186, v130, v131
	v_cvt_pk_bf16_f32 v187, v132, v133
	s_mov_b64 vcc, s[84:85]
	v_cndmask_b32_dpp v216, v184, v168, vcc quad_perm:[1,0,3,2] row_mask:0xf bank_mask:0xf
	v_cndmask_b32_dpp v217, v185, v169, vcc quad_perm:[1,0,3,2] row_mask:0xf bank_mask:0xf
	v_cndmask_b32_dpp v218, v186, v170, vcc quad_perm:[1,0,3,2] row_mask:0xf bank_mask:0xf
	v_cndmask_b32_dpp v219, v187, v171, vcc quad_perm:[1,0,3,2] row_mask:0xf bank_mask:0xf
	s_mov_b64 vcc, s[62:63]
	v_cndmask_b32_dpp v220, v168, v184, vcc quad_perm:[1,0,3,2] row_mask:0xf bank_mask:0xf
	v_cndmask_b32_dpp v221, v169, v185, vcc quad_perm:[1,0,3,2] row_mask:0xf bank_mask:0xf
	v_cndmask_b32_dpp v222, v170, v186, vcc quad_perm:[1,0,3,2] row_mask:0xf bank_mask:0xf
	v_cndmask_b32_dpp v223, v171, v187, vcc quad_perm:[1,0,3,2] row_mask:0xf bank_mask:0xf
	s_add_u32 s80, s10, 0x0
	s_addc_u32 s81, s11, 0
	s_add_u32 s82, s10, 0x2000
	s_addc_u32 s83, s11, 0
	global_store_dwordx4 v177, v[216:219], s[80:81]
	global_store_dwordx4 v177, v[220:223], s[82:83]
	v_pk_fma_f32 v[126:127], v[126:127], v[174:175], v[26:27] op_sel_hi:[1,0,1]
	v_pk_fma_f32 v[128:129], v[128:129], v[174:175], v[28:29] op_sel_hi:[1,0,1]
	v_pk_fma_f32 v[122:123], v[122:123], v[174:175], v[30:31] op_sel_hi:[1,0,1]
	v_pk_fma_f32 v[124:125], v[124:125], v[174:175], v[32:33] op_sel_hi:[1,0,1]
	v_cvt_pk_bf16_f32 v168, v126, v127
	v_cvt_pk_bf16_f32 v169, v128, v129
	v_cvt_pk_bf16_f32 v170, v122, v123
	v_cvt_pk_bf16_f32 v171, v124, v125
	v_pk_fma_f32 v[118:119], v[118:119], v[174:175], v[42:43] op_sel_hi:[1,0,1]
	v_pk_fma_f32 v[120:121], v[120:121], v[174:175], v[44:45] op_sel_hi:[1,0,1]
	v_pk_fma_f32 v[114:115], v[114:115], v[174:175], v[46:47] op_sel_hi:[1,0,1]
	v_pk_fma_f32 v[116:117], v[116:117], v[174:175], v[48:49] op_sel_hi:[1,0,1]
	v_cvt_pk_bf16_f32 v184, v118, v119
	v_cvt_pk_bf16_f32 v185, v120, v121
	v_cvt_pk_bf16_f32 v186, v114, v115
	v_cvt_pk_bf16_f32 v187, v116, v117
	s_mov_b64 vcc, s[84:85]
	v_cndmask_b32_dpp v216, v184, v168, vcc quad_perm:[1,0,3,2] row_mask:0xf bank_mask:0xf
	v_cndmask_b32_dpp v217, v185, v169, vcc quad_perm:[1,0,3,2] row_mask:0xf bank_mask:0xf
	v_cndmask_b32_dpp v218, v186, v170, vcc quad_perm:[1,0,3,2] row_mask:0xf bank_mask:0xf
	v_cndmask_b32_dpp v219, v187, v171, vcc quad_perm:[1,0,3,2] row_mask:0xf bank_mask:0xf
	s_mov_b64 vcc, s[62:63]
	v_cndmask_b32_dpp v220, v168, v184, vcc quad_perm:[1,0,3,2] row_mask:0xf bank_mask:0xf
	v_cndmask_b32_dpp v221, v169, v185, vcc quad_perm:[1,0,3,2] row_mask:0xf bank_mask:0xf
	v_cndmask_b32_dpp v222, v170, v186, vcc quad_perm:[1,0,3,2] row_mask:0xf bank_mask:0xf
	v_cndmask_b32_dpp v223, v171, v187, vcc quad_perm:[1,0,3,2] row_mask:0xf bank_mask:0xf
	s_add_u32 s80, s10, 0x20000
	s_addc_u32 s81, s11, 0
	s_add_u32 s82, s10, 0x22000
	s_addc_u32 s83, s11, 0
	global_store_dwordx4 v177, v[216:219], s[80:81]
	global_store_dwordx4 v177, v[220:223], s[82:83]
	v_pk_fma_f32 v[110:111], v[110:111], v[176:177], v[26:27] op_sel_hi:[1,0,1]
	v_pk_fma_f32 v[112:113], v[112:113], v[176:177], v[28:29] op_sel_hi:[1,0,1]
	v_pk_fma_f32 v[106:107], v[106:107], v[176:177], v[30:31] op_sel_hi:[1,0,1]
	v_pk_fma_f32 v[108:109], v[108:109], v[176:177], v[32:33] op_sel_hi:[1,0,1]
	v_cvt_pk_bf16_f32 v168, v110, v111
	v_cvt_pk_bf16_f32 v169, v112, v113
	v_cvt_pk_bf16_f32 v170, v106, v107
	v_cvt_pk_bf16_f32 v171, v108, v109
	v_pk_fma_f32 v[102:103], v[102:103], v[176:177], v[42:43] op_sel_hi:[1,0,1]
	v_pk_fma_f32 v[104:105], v[104:105], v[176:177], v[44:45] op_sel_hi:[1,0,1]
	v_pk_fma_f32 v[98:99], v[98:99], v[176:177], v[46:47] op_sel_hi:[1,0,1]
	v_pk_fma_f32 v[100:101], v[100:101], v[176:177], v[48:49] op_sel_hi:[1,0,1]
	v_cvt_pk_bf16_f32 v184, v102, v103
	v_cvt_pk_bf16_f32 v185, v104, v105
	v_cvt_pk_bf16_f32 v186, v98, v99
	v_cvt_pk_bf16_f32 v187, v100, v101
	s_mov_b64 vcc, s[84:85]
	v_cndmask_b32_dpp v216, v184, v168, vcc quad_perm:[1,0,3,2] row_mask:0xf bank_mask:0xf
	v_cndmask_b32_dpp v217, v185, v169, vcc quad_perm:[1,0,3,2] row_mask:0xf bank_mask:0xf
	v_cndmask_b32_dpp v218, v186, v170, vcc quad_perm:[1,0,3,2] row_mask:0xf bank_mask:0xf
	v_cndmask_b32_dpp v219, v187, v171, vcc quad_perm:[1,0,3,2] row_mask:0xf bank_mask:0xf
	s_mov_b64 vcc, s[62:63]
	v_cndmask_b32_dpp v220, v168, v184, vcc quad_perm:[1,0,3,2] row_mask:0xf bank_mask:0xf
	v_cndmask_b32_dpp v221, v169, v185, vcc quad_perm:[1,0,3,2] row_mask:0xf bank_mask:0xf
	v_cndmask_b32_dpp v222, v170, v186, vcc quad_perm:[1,0,3,2] row_mask:0xf bank_mask:0xf
	v_cndmask_b32_dpp v223, v171, v187, vcc quad_perm:[1,0,3,2] row_mask:0xf bank_mask:0xf
	s_add_u32 s80, s10, 0x40000
	s_addc_u32 s81, s11, 0
	s_add_u32 s82, s10, 0x42000
	s_addc_u32 s83, s11, 0
	global_store_dwordx4 v177, v[216:219], s[80:81]
	global_store_dwordx4 v177, v[220:223], s[82:83]
	v_pk_fma_f32 v[94:95], v[94:95], v[178:179], v[26:27] op_sel_hi:[1,0,1]
	v_pk_fma_f32 v[96:97], v[96:97], v[178:179], v[28:29] op_sel_hi:[1,0,1]
	v_pk_fma_f32 v[90:91], v[90:91], v[178:179], v[30:31] op_sel_hi:[1,0,1]
	v_pk_fma_f32 v[92:93], v[92:93], v[178:179], v[32:33] op_sel_hi:[1,0,1]
	v_cvt_pk_bf16_f32 v168, v94, v95
	v_cvt_pk_bf16_f32 v169, v96, v97
	v_cvt_pk_bf16_f32 v170, v90, v91
	v_cvt_pk_bf16_f32 v171, v92, v93
	v_pk_fma_f32 v[86:87], v[86:87], v[178:179], v[42:43] op_sel_hi:[1,0,1]
	v_pk_fma_f32 v[88:89], v[88:89], v[178:179], v[44:45] op_sel_hi:[1,0,1]
	v_pk_fma_f32 v[82:83], v[82:83], v[178:179], v[46:47] op_sel_hi:[1,0,1]
	v_pk_fma_f32 v[84:85], v[84:85], v[178:179], v[48:49] op_sel_hi:[1,0,1]
	v_cvt_pk_bf16_f32 v184, v86, v87
	v_cvt_pk_bf16_f32 v185, v88, v89
	v_cvt_pk_bf16_f32 v186, v82, v83
	v_cvt_pk_bf16_f32 v187, v84, v85
	s_mov_b64 vcc, s[84:85]
	v_cndmask_b32_dpp v216, v184, v168, vcc quad_perm:[1,0,3,2] row_mask:0xf bank_mask:0xf
	v_cndmask_b32_dpp v217, v185, v169, vcc quad_perm:[1,0,3,2] row_mask:0xf bank_mask:0xf
	v_cndmask_b32_dpp v218, v186, v170, vcc quad_perm:[1,0,3,2] row_mask:0xf bank_mask:0xf
	v_cndmask_b32_dpp v219, v187, v171, vcc quad_perm:[1,0,3,2] row_mask:0xf bank_mask:0xf
	s_mov_b64 vcc, s[62:63]
	v_cndmask_b32_dpp v220, v168, v184, vcc quad_perm:[1,0,3,2] row_mask:0xf bank_mask:0xf
	v_cndmask_b32_dpp v221, v169, v185, vcc quad_perm:[1,0,3,2] row_mask:0xf bank_mask:0xf
	v_cndmask_b32_dpp v222, v170, v186, vcc quad_perm:[1,0,3,2] row_mask:0xf bank_mask:0xf
	v_cndmask_b32_dpp v223, v171, v187, vcc quad_perm:[1,0,3,2] row_mask:0xf bank_mask:0xf
	s_add_u32 s80, s10, 0x60000
	s_addc_u32 s81, s11, 0
	s_add_u32 s82, s10, 0x62000
	s_addc_u32 s83, s11, 0
	global_store_dwordx4 v177, v[216:219], s[80:81]
	global_store_dwordx4 v177, v[220:223], s[82:83]
	v_pk_fma_f32 v[78:79], v[78:79], v[180:181], v[26:27] op_sel_hi:[1,0,1]
	v_pk_fma_f32 v[80:81], v[80:81], v[180:181], v[28:29] op_sel_hi:[1,0,1]
	v_pk_fma_f32 v[74:75], v[74:75], v[180:181], v[30:31] op_sel_hi:[1,0,1]
	v_pk_fma_f32 v[76:77], v[76:77], v[180:181], v[32:33] op_sel_hi:[1,0,1]
	v_cvt_pk_bf16_f32 v168, v78, v79
	v_cvt_pk_bf16_f32 v169, v80, v81
	v_cvt_pk_bf16_f32 v170, v74, v75
	v_cvt_pk_bf16_f32 v171, v76, v77
	v_pk_fma_f32 v[70:71], v[70:71], v[180:181], v[42:43] op_sel_hi:[1,0,1]
	v_pk_fma_f32 v[72:73], v[72:73], v[180:181], v[44:45] op_sel_hi:[1,0,1]
	v_pk_fma_f32 v[66:67], v[66:67], v[180:181], v[46:47] op_sel_hi:[1,0,1]
	v_pk_fma_f32 v[68:69], v[68:69], v[180:181], v[48:49] op_sel_hi:[1,0,1]
	v_cvt_pk_bf16_f32 v184, v70, v71
	v_cvt_pk_bf16_f32 v185, v72, v73
	v_cvt_pk_bf16_f32 v186, v66, v67
	v_cvt_pk_bf16_f32 v187, v68, v69
	s_mov_b64 vcc, s[84:85]
	v_cndmask_b32_dpp v216, v184, v168, vcc quad_perm:[1,0,3,2] row_mask:0xf bank_mask:0xf
	v_cndmask_b32_dpp v217, v185, v169, vcc quad_perm:[1,0,3,2] row_mask:0xf bank_mask:0xf
	v_cndmask_b32_dpp v218, v186, v170, vcc quad_perm:[1,0,3,2] row_mask:0xf bank_mask:0xf
	v_cndmask_b32_dpp v219, v187, v171, vcc quad_perm:[1,0,3,2] row_mask:0xf bank_mask:0xf
	s_mov_b64 vcc, s[62:63]
	v_cndmask_b32_dpp v220, v168, v184, vcc quad_perm:[1,0,3,2] row_mask:0xf bank_mask:0xf
	v_cndmask_b32_dpp v221, v169, v185, vcc quad_perm:[1,0,3,2] row_mask:0xf bank_mask:0xf
	v_cndmask_b32_dpp v222, v170, v186, vcc quad_perm:[1,0,3,2] row_mask:0xf bank_mask:0xf
	v_cndmask_b32_dpp v223, v171, v187, vcc quad_perm:[1,0,3,2] row_mask:0xf bank_mask:0xf
	s_add_u32 s80, s10, 0x100000
	s_addc_u32 s81, s11, 0
	s_add_u32 s82, s10, 0x102000
	s_addc_u32 s83, s11, 0
	global_store_dwordx4 v177, v[216:219], s[80:81]
	global_store_dwordx4 v177, v[220:223], s[82:83]
	v_pk_fma_f32 v[62:63], v[62:63], v[182:183], v[26:27] op_sel_hi:[1,0,1]
	v_pk_fma_f32 v[64:65], v[64:65], v[182:183], v[28:29] op_sel_hi:[1,0,1]
	v_pk_fma_f32 v[58:59], v[58:59], v[182:183], v[30:31] op_sel_hi:[1,0,1]
	v_pk_fma_f32 v[60:61], v[60:61], v[182:183], v[32:33] op_sel_hi:[1,0,1]
	v_cvt_pk_bf16_f32 v168, v62, v63
	v_cvt_pk_bf16_f32 v169, v64, v65
	v_cvt_pk_bf16_f32 v170, v58, v59
	v_cvt_pk_bf16_f32 v171, v60, v61
	v_pk_fma_f32 v[54:55], v[54:55], v[182:183], v[42:43] op_sel_hi:[1,0,1]
	v_pk_fma_f32 v[56:57], v[56:57], v[182:183], v[44:45] op_sel_hi:[1,0,1]
	v_pk_fma_f32 v[50:51], v[50:51], v[182:183], v[46:47] op_sel_hi:[1,0,1]
	v_pk_fma_f32 v[52:53], v[52:53], v[182:183], v[48:49] op_sel_hi:[1,0,1]
	v_cvt_pk_bf16_f32 v184, v54, v55
	v_cvt_pk_bf16_f32 v185, v56, v57
	v_cvt_pk_bf16_f32 v186, v50, v51
	v_cvt_pk_bf16_f32 v187, v52, v53
	s_mov_b64 vcc, s[84:85]
	v_cndmask_b32_dpp v216, v184, v168, vcc quad_perm:[1,0,3,2] row_mask:0xf bank_mask:0xf
	v_cndmask_b32_dpp v217, v185, v169, vcc quad_perm:[1,0,3,2] row_mask:0xf bank_mask:0xf
	v_cndmask_b32_dpp v218, v186, v170, vcc quad_perm:[1,0,3,2] row_mask:0xf bank_mask:0xf
	v_cndmask_b32_dpp v219, v187, v171, vcc quad_perm:[1,0,3,2] row_mask:0xf bank_mask:0xf
	s_mov_b64 vcc, s[62:63]
	v_cndmask_b32_dpp v220, v168, v184, vcc quad_perm:[1,0,3,2] row_mask:0xf bank_mask:0xf
	v_cndmask_b32_dpp v221, v169, v185, vcc quad_perm:[1,0,3,2] row_mask:0xf bank_mask:0xf
	v_cndmask_b32_dpp v222, v170, v186, vcc quad_perm:[1,0,3,2] row_mask:0xf bank_mask:0xf
	v_cndmask_b32_dpp v223, v171, v187, vcc quad_perm:[1,0,3,2] row_mask:0xf bank_mask:0xf
	s_add_u32 s80, s10, 0x120000
	s_addc_u32 s81, s11, 0
	s_add_u32 s82, s10, 0x122000
	s_addc_u32 s83, s11, 0
	global_store_dwordx4 v177, v[216:219], s[80:81]
	global_store_dwordx4 v177, v[220:223], s[82:83]
	v_pk_fma_f32 v[38:39], v[38:39], v[188:189], v[26:27] op_sel_hi:[1,0,1]
	v_pk_fma_f32 v[40:41], v[40:41], v[188:189], v[28:29] op_sel_hi:[1,0,1]
	v_pk_fma_f32 v[34:35], v[34:35], v[188:189], v[30:31] op_sel_hi:[1,0,1]
	v_pk_fma_f32 v[36:37], v[36:37], v[188:189], v[32:33] op_sel_hi:[1,0,1]
	v_cvt_pk_bf16_f32 v168, v38, v39
	v_cvt_pk_bf16_f32 v169, v40, v41
	v_cvt_pk_bf16_f32 v170, v34, v35
	v_cvt_pk_bf16_f32 v171, v36, v37
	v_pk_fma_f32 v[22:23], v[22:23], v[188:189], v[42:43] op_sel_hi:[1,0,1]
	v_pk_fma_f32 v[24:25], v[24:25], v[188:189], v[44:45] op_sel_hi:[1,0,1]
	v_pk_fma_f32 v[18:19], v[18:19], v[188:189], v[46:47] op_sel_hi:[1,0,1]
	v_pk_fma_f32 v[20:21], v[20:21], v[188:189], v[48:49] op_sel_hi:[1,0,1]
	v_cvt_pk_bf16_f32 v184, v22, v23
	v_cvt_pk_bf16_f32 v185, v24, v25
	v_cvt_pk_bf16_f32 v186, v18, v19
	v_cvt_pk_bf16_f32 v187, v20, v21
	s_mov_b64 vcc, s[84:85]
	v_cndmask_b32_dpp v216, v184, v168, vcc quad_perm:[1,0,3,2] row_mask:0xf bank_mask:0xf
	v_cndmask_b32_dpp v217, v185, v169, vcc quad_perm:[1,0,3,2] row_mask:0xf bank_mask:0xf
	v_cndmask_b32_dpp v218, v186, v170, vcc quad_perm:[1,0,3,2] row_mask:0xf bank_mask:0xf
	v_cndmask_b32_dpp v219, v187, v171, vcc quad_perm:[1,0,3,2] row_mask:0xf bank_mask:0xf
	s_mov_b64 vcc, s[62:63]
	v_cndmask_b32_dpp v220, v168, v184, vcc quad_perm:[1,0,3,2] row_mask:0xf bank_mask:0xf
	v_cndmask_b32_dpp v221, v169, v185, vcc quad_perm:[1,0,3,2] row_mask:0xf bank_mask:0xf
	v_cndmask_b32_dpp v222, v170, v186, vcc quad_perm:[1,0,3,2] row_mask:0xf bank_mask:0xf
	v_cndmask_b32_dpp v223, v171, v187, vcc quad_perm:[1,0,3,2] row_mask:0xf bank_mask:0xf
	s_add_u32 s80, s10, 0x140000
	s_addc_u32 s81, s11, 0
	s_add_u32 s82, s10, 0x142000
	s_addc_u32 s83, s11, 0
	global_store_dwordx4 v177, v[216:219], s[80:81]
	global_store_dwordx4 v177, v[220:223], s[82:83]
	v_pk_fma_f32 v[14:15], v[14:15], v[240:241], v[26:27] op_sel_hi:[1,0,1]
	v_pk_fma_f32 v[16:17], v[16:17], v[240:241], v[28:29] op_sel_hi:[1,0,1]
	v_pk_fma_f32 v[10:11], v[10:11], v[240:241], v[30:31] op_sel_hi:[1,0,1]
	v_pk_fma_f32 v[12:13], v[12:13], v[240:241], v[32:33] op_sel_hi:[1,0,1]
	v_cvt_pk_bf16_f32 v168, v14, v15
	v_cvt_pk_bf16_f32 v169, v16, v17
	v_cvt_pk_bf16_f32 v170, v10, v11
	v_cvt_pk_bf16_f32 v171, v12, v13
	v_pk_fma_f32 v[6:7], v[6:7], v[240:241], v[42:43] op_sel_hi:[1,0,1]
	v_pk_fma_f32 v[8:9], v[8:9], v[240:241], v[44:45] op_sel_hi:[1,0,1]
	v_pk_fma_f32 v[2:3], v[2:3], v[240:241], v[46:47] op_sel_hi:[1,0,1]
	v_pk_fma_f32 v[4:5], v[4:5], v[240:241], v[48:49] op_sel_hi:[1,0,1]
	v_cvt_pk_bf16_f32 v184, v6, v7
	v_cvt_pk_bf16_f32 v185, v8, v9
	v_cvt_pk_bf16_f32 v186, v2, v3
	v_cvt_pk_bf16_f32 v187, v4, v5
	s_mov_b64 vcc, s[84:85]
	v_cndmask_b32_dpp v216, v184, v168, vcc quad_perm:[1,0,3,2] row_mask:0xf bank_mask:0xf
	v_cndmask_b32_dpp v217, v185, v169, vcc quad_perm:[1,0,3,2] row_mask:0xf bank_mask:0xf
	v_cndmask_b32_dpp v218, v186, v170, vcc quad_perm:[1,0,3,2] row_mask:0xf bank_mask:0xf
	v_cndmask_b32_dpp v219, v187, v171, vcc quad_perm:[1,0,3,2] row_mask:0xf bank_mask:0xf
	s_mov_b64 vcc, s[62:63]
	v_cndmask_b32_dpp v220, v168, v184, vcc quad_perm:[1,0,3,2] row_mask:0xf bank_mask:0xf
	v_cndmask_b32_dpp v221, v169, v185, vcc quad_perm:[1,0,3,2] row_mask:0xf bank_mask:0xf
	v_cndmask_b32_dpp v222, v170, v186, vcc quad_perm:[1,0,3,2] row_mask:0xf bank_mask:0xf
	v_cndmask_b32_dpp v223, v171, v187, vcc quad_perm:[1,0,3,2] row_mask:0xf bank_mask:0xf
	s_add_u32 s80, s10, 0x160000
	s_addc_u32 s81, s11, 0
	s_add_u32 s82, s10, 0x162000
	s_addc_u32 s83, s11, 0
	global_store_dwordx4 v177, v[216:219], s[80:81]
	global_store_dwordx4 v177, v[220:223], s[82:83]
	s_branch .Lact1_hgin_done
.Lact1_hgin_kk:
	v_lshlrev_b32_e32 v189, 2, v189
	s_add_u32 s80, s18, 0xfffff000
	s_addc_u32 s81, s19, -1
	global_load_dwordx4 v[224:227], v189, s[80:81] offset:0
	global_load_dwordx4 v[228:231], v189, s[80:81] offset:16
	global_load_dwordx4 v[232:235], v189, s[80:81] offset:128
	global_load_dwordx4 v[236:239], v189, s[80:81] offset:144
	s_waitcnt vmcnt(0) lgkmcnt(0)
	v_sub_f32_e32 v224, 1.0, v224
	v_sub_f32_e32 v225, 1.0, v225
	v_sub_f32_e32 v226, 1.0, v226
	v_sub_f32_e32 v227, 1.0, v227
	v_sub_f32_e32 v228, 1.0, v228
	v_sub_f32_e32 v229, 1.0, v229
	v_sub_f32_e32 v230, 1.0, v230
	v_sub_f32_e32 v231, 1.0, v231
	v_sub_f32_e32 v232, 1.0, v232
	v_sub_f32_e32 v233, 1.0, v233
	v_sub_f32_e32 v234, 1.0, v234
	v_sub_f32_e32 v235, 1.0, v235
	v_sub_f32_e32 v236, 1.0, v236
	v_sub_f32_e32 v237, 1.0, v237
	v_sub_f32_e32 v238, 1.0, v238
	v_sub_f32_e32 v239, 1.0, v239
	v_pk_fma_f32 v[142:143], v[142:143], v[172:173], v[26:27] op_sel_hi:[1,0,1]
	v_pk_fma_f32 v[144:145], v[144:145], v[172:173], v[28:29] op_sel_hi:[1,0,1]
	v_pk_fma_f32 v[138:139], v[138:139], v[172:173], v[30:31] op_sel_hi:[1,0,1]
	v_pk_fma_f32 v[140:141], v[140:141], v[172:173], v[32:33] op_sel_hi:[1,0,1]
	v_pk_mul_f32 v[216:217], v[142:143], s[90:91] op_sel_hi:[1,0]
	v_pk_mul_f32 v[218:219], v[144:145], s[90:91] op_sel_hi:[1,0]
	v_pk_mul_f32 v[220:221], v[138:139], s[90:91] op_sel_hi:[1,0]
	v_pk_mul_f32 v[222:223], v[140:141], s[90:91] op_sel_hi:[1,0]
	v_exp_f32_e32 v216, v216
	v_exp_f32_e32 v217, v217
	v_exp_f32_e32 v218, v218
	v_exp_f32_e32 v219, v219
	v_exp_f32_e32 v220, v220
	v_exp_f32_e32 v221, v221
	v_exp_f32_e32 v222, v222
	v_exp_f32_e32 v223, v223
	v_pk_add_f32 v[216:217], v[216:217], 1.0 op_sel_hi:[1,0]
	v_pk_add_f32 v[218:219], v[218:219], 1.0 op_sel_hi:[1,0]
	v_pk_add_f32 v[220:221], v[220:221], 1.0 op_sel_hi:[1,0]
	v_pk_add_f32 v[222:223], v[222:223], 1.0 op_sel_hi:[1,0]
	v_rcp_f32_e32 v216, v216
	v_rcp_f32_e32 v217, v217
	v_rcp_f32_e32 v218, v218
	v_rcp_f32_e32 v219, v219
	v_rcp_f32_e32 v220, v220
	v_rcp_f32_e32 v221, v221
	v_rcp_f32_e32 v222, v222
	v_rcp_f32_e32 v223, v223
	v_pk_mul_f32 v[216:217], v[216:217], v[224:225]
	v_pk_mul_f32 v[218:219], v[218:219], v[226:227]
	v_pk_mul_f32 v[220:221], v[220:221], v[228:229]
	v_pk_mul_f32 v[222:223], v[222:223], v[230:231]
	v_cvt_pk_f16_f32 v168, v216, v217
	v_cvt_pk_f16_f32 v169, v218, v219
	v_cvt_pk_f16_f32 v170, v220, v221
	v_cvt_pk_f16_f32 v171, v222, v223
	v_pk_fma_f32 v[134:135], v[134:135], v[172:173], v[42:43] op_sel_hi:[1,0,1]
	v_pk_fma_f32 v[136:137], v[136:137], v[172:173], v[44:45] op_sel_hi:[1,0,1]
	v_pk_fma_f32 v[130:131], v[130:131], v[172:173], v[46:47] op_sel_hi:[1,0,1]
	v_pk_fma_f32 v[132:133], v[132:133], v[172:173], v[48:49] op_sel_hi:[1,0,1]
	v_pk_mul_f32 v[216:217], v[134:135], s[90:91] op_sel_hi:[1,0]
	v_pk_mul_f32 v[218:219], v[136:137], s[90:91] op_sel_hi:[1,0]
	v_pk_mul_f32 v[220:221], v[130:131], s[90:91] op_sel_hi:[1,0]
	v_pk_mul_f32 v[222:223], v[132:133], s[90:91] op_sel_hi:[1,0]
	v_exp_f32_e32 v216, v216
	v_exp_f32_e32 v217, v217
	v_exp_f32_e32 v218, v218
	v_exp_f32_e32 v219, v219
	v_exp_f32_e32 v220, v220
	v_exp_f32_e32 v221, v221
	v_exp_f32_e32 v222, v222
	v_exp_f32_e32 v223, v223
	v_pk_add_f32 v[216:217], v[216:217], 1.0 op_sel_hi:[1,0]
	v_pk_add_f32 v[218:219], v[218:219], 1.0 op_sel_hi:[1,0]
	v_pk_add_f32 v[220:221], v[220:221], 1.0 op_sel_hi:[1,0]
	v_pk_add_f32 v[222:223], v[222:223], 1.0 op_sel_hi:[1,0]
	v_rcp_f32_e32 v216, v216
	v_rcp_f32_e32 v217, v217
	v_rcp_f32_e32 v218, v218
	v_rcp_f32_e32 v219, v219
	v_rcp_f32_e32 v220, v220
	v_rcp_f32_e32 v221, v221
	v_rcp_f32_e32 v222, v222
	v_rcp_f32_e32 v223, v223
	v_pk_mul_f32 v[216:217], v[216:217], v[232:233]
	v_pk_mul_f32 v[218:219], v[218:219], v[234:235]
	v_pk_mul_f32 v[220:221], v[220:221], v[236:237]
	v_pk_mul_f32 v[222:223], v[222:223], v[238:239]
	v_cvt_pk_f16_f32 v184, v216, v217
	v_cvt_pk_f16_f32 v185, v218, v219
	v_cvt_pk_f16_f32 v186, v220, v221
	v_cvt_pk_f16_f32 v187, v222, v223
	s_mov_b64 vcc, s[84:85]
	v_cndmask_b32_dpp v216, v184, v168, vcc quad_perm:[1,0,3,2] row_mask:0xf bank_mask:0xf
	v_cndmask_b32_dpp v217, v185, v169, vcc quad_perm:[1,0,3,2] row_mask:0xf bank_mask:0xf
	v_cndmask_b32_dpp v218, v186, v170, vcc quad_perm:[1,0,3,2] row_mask:0xf bank_mask:0xf
	v_cndmask_b32_dpp v219, v187, v171, vcc quad_perm:[1,0,3,2] row_mask:0xf bank_mask:0xf
	s_mov_b64 vcc, s[62:63]
	v_cndmask_b32_dpp v220, v168, v184, vcc quad_perm:[1,0,3,2] row_mask:0xf bank_mask:0xf
	v_cndmask_b32_dpp v221, v169, v185, vcc quad_perm:[1,0,3,2] row_mask:0xf bank_mask:0xf
	v_cndmask_b32_dpp v222, v170, v186, vcc quad_perm:[1,0,3,2] row_mask:0xf bank_mask:0xf
	v_cndmask_b32_dpp v223, v171, v187, vcc quad_perm:[1,0,3,2] row_mask:0xf bank_mask:0xf
	s_add_u32 s80, s10, 0x0
	s_addc_u32 s81, s11, 0
	s_add_u32 s82, s10, 0x2000
	s_addc_u32 s83, s11, 0
	global_store_dwordx4 v177, v[216:219], s[80:81]
	global_store_dwordx4 v177, v[220:223], s[82:83]
	v_pk_fma_f32 v[126:127], v[126:127], v[174:175], v[26:27] op_sel_hi:[1,0,1]
	v_pk_fma_f32 v[128:129], v[128:129], v[174:175], v[28:29] op_sel_hi:[1,0,1]
	v_pk_fma_f32 v[122:123], v[122:123], v[174:175], v[30:31] op_sel_hi:[1,0,1]
	v_pk_fma_f32 v[124:125], v[124:125], v[174:175], v[32:33] op_sel_hi:[1,0,1]
	v_pk_mul_f32 v[216:217], v[126:127], s[90:91] op_sel_hi:[1,0]
	v_pk_mul_f32 v[218:219], v[128:129], s[90:91] op_sel_hi:[1,0]
	v_pk_mul_f32 v[220:221], v[122:123], s[90:91] op_sel_hi:[1,0]
	v_pk_mul_f32 v[222:223], v[124:125], s[90:91] op_sel_hi:[1,0]
	v_exp_f32_e32 v216, v216
	v_exp_f32_e32 v217, v217
	v_exp_f32_e32 v218, v218
	v_exp_f32_e32 v219, v219
	v_exp_f32_e32 v220, v220
	v_exp_f32_e32 v221, v221
	v_exp_f32_e32 v222, v222
	v_exp_f32_e32 v223, v223
	v_pk_add_f32 v[216:217], v[216:217], 1.0 op_sel_hi:[1,0]
	v_pk_add_f32 v[218:219], v[218:219], 1.0 op_sel_hi:[1,0]
	v_pk_add_f32 v[220:221], v[220:221], 1.0 op_sel_hi:[1,0]
	v_pk_add_f32 v[222:223], v[222:223], 1.0 op_sel_hi:[1,0]
	v_rcp_f32_e32 v216, v216
	v_rcp_f32_e32 v217, v217
	v_rcp_f32_e32 v218, v218
	v_rcp_f32_e32 v219, v219
	v_rcp_f32_e32 v220, v220
	v_rcp_f32_e32 v221, v221
	v_rcp_f32_e32 v222, v222
	v_rcp_f32_e32 v223, v223
	v_pk_mul_f32 v[216:217], v[216:217], v[224:225]
	v_pk_mul_f32 v[218:219], v[218:219], v[226:227]
	v_pk_mul_f32 v[220:221], v[220:221], v[228:229]
	v_pk_mul_f32 v[222:223], v[222:223], v[230:231]
	v_cvt_pk_f16_f32 v168, v216, v217
	v_cvt_pk_f16_f32 v169, v218, v219
	v_cvt_pk_f16_f32 v170, v220, v221
	v_cvt_pk_f16_f32 v171, v222, v223
	v_pk_fma_f32 v[118:119], v[118:119], v[174:175], v[42:43] op_sel_hi:[1,0,1]
	v_pk_fma_f32 v[120:121], v[120:121], v[174:175], v[44:45] op_sel_hi:[1,0,1]
	v_pk_fma_f32 v[114:115], v[114:115], v[174:175], v[46:47] op_sel_hi:[1,0,1]
	v_pk_fma_f32 v[116:117], v[116:117], v[174:175], v[48:49] op_sel_hi:[1,0,1]
	v_pk_mul_f32 v[216:217], v[118:119], s[90:91] op_sel_hi:[1,0]
	v_pk_mul_f32 v[218:219], v[120:121], s[90:91] op_sel_hi:[1,0]
	v_pk_mul_f32 v[220:221], v[114:115], s[90:91] op_sel_hi:[1,0]
	v_pk_mul_f32 v[222:223], v[116:117], s[90:91] op_sel_hi:[1,0]
	v_exp_f32_e32 v216, v216
	v_exp_f32_e32 v217, v217
	v_exp_f32_e32 v218, v218
	v_exp_f32_e32 v219, v219
	v_exp_f32_e32 v220, v220
	v_exp_f32_e32 v221, v221
	v_exp_f32_e32 v222, v222
	v_exp_f32_e32 v223, v223
	v_pk_add_f32 v[216:217], v[216:217], 1.0 op_sel_hi:[1,0]
	v_pk_add_f32 v[218:219], v[218:219], 1.0 op_sel_hi:[1,0]
	v_pk_add_f32 v[220:221], v[220:221], 1.0 op_sel_hi:[1,0]
	v_pk_add_f32 v[222:223], v[222:223], 1.0 op_sel_hi:[1,0]
	v_rcp_f32_e32 v216, v216
	v_rcp_f32_e32 v217, v217
	v_rcp_f32_e32 v218, v218
	v_rcp_f32_e32 v219, v219
	v_rcp_f32_e32 v220, v220
	v_rcp_f32_e32 v221, v221
	v_rcp_f32_e32 v222, v222
	v_rcp_f32_e32 v223, v223
	v_pk_mul_f32 v[216:217], v[216:217], v[232:233]
	v_pk_mul_f32 v[218:219], v[218:219], v[234:235]
	v_pk_mul_f32 v[220:221], v[220:221], v[236:237]
	v_pk_mul_f32 v[222:223], v[222:223], v[238:239]
	v_cvt_pk_f16_f32 v184, v216, v217
	v_cvt_pk_f16_f32 v185, v218, v219
	v_cvt_pk_f16_f32 v186, v220, v221
	v_cvt_pk_f16_f32 v187, v222, v223
	s_mov_b64 vcc, s[84:85]
	v_cndmask_b32_dpp v216, v184, v168, vcc quad_perm:[1,0,3,2] row_mask:0xf bank_mask:0xf
	v_cndmask_b32_dpp v217, v185, v169, vcc quad_perm:[1,0,3,2] row_mask:0xf bank_mask:0xf
	v_cndmask_b32_dpp v218, v186, v170, vcc quad_perm:[1,0,3,2] row_mask:0xf bank_mask:0xf
	v_cndmask_b32_dpp v219, v187, v171, vcc quad_perm:[1,0,3,2] row_mask:0xf bank_mask:0xf
	s_mov_b64 vcc, s[62:63]
	v_cndmask_b32_dpp v220, v168, v184, vcc quad_perm:[1,0,3,2] row_mask:0xf bank_mask:0xf
	v_cndmask_b32_dpp v221, v169, v185, vcc quad_perm:[1,0,3,2] row_mask:0xf bank_mask:0xf
	v_cndmask_b32_dpp v222, v170, v186, vcc quad_perm:[1,0,3,2] row_mask:0xf bank_mask:0xf
	v_cndmask_b32_dpp v223, v171, v187, vcc quad_perm:[1,0,3,2] row_mask:0xf bank_mask:0xf
	s_add_u32 s80, s10, 0x20000
	s_addc_u32 s81, s11, 0
	s_add_u32 s82, s10, 0x22000
	s_addc_u32 s83, s11, 0
	global_store_dwordx4 v177, v[216:219], s[80:81]
	global_store_dwordx4 v177, v[220:223], s[82:83]
	v_pk_fma_f32 v[110:111], v[110:111], v[176:177], v[26:27] op_sel_hi:[1,0,1]
	v_pk_fma_f32 v[112:113], v[112:113], v[176:177], v[28:29] op_sel_hi:[1,0,1]
	v_pk_fma_f32 v[106:107], v[106:107], v[176:177], v[30:31] op_sel_hi:[1,0,1]
	v_pk_fma_f32 v[108:109], v[108:109], v[176:177], v[32:33] op_sel_hi:[1,0,1]
	v_pk_mul_f32 v[216:217], v[110:111], s[90:91] op_sel_hi:[1,0]
	v_pk_mul_f32 v[218:219], v[112:113], s[90:91] op_sel_hi:[1,0]
	v_pk_mul_f32 v[220:221], v[106:107], s[90:91] op_sel_hi:[1,0]
	v_pk_mul_f32 v[222:223], v[108:109], s[90:91] op_sel_hi:[1,0]
	v_exp_f32_e32 v216, v216
	v_exp_f32_e32 v217, v217
	v_exp_f32_e32 v218, v218
	v_exp_f32_e32 v219, v219
	v_exp_f32_e32 v220, v220
	v_exp_f32_e32 v221, v221
	v_exp_f32_e32 v222, v222
	v_exp_f32_e32 v223, v223
	v_pk_add_f32 v[216:217], v[216:217], 1.0 op_sel_hi:[1,0]
	v_pk_add_f32 v[218:219], v[218:219], 1.0 op_sel_hi:[1,0]
	v_pk_add_f32 v[220:221], v[220:221], 1.0 op_sel_hi:[1,0]
	v_pk_add_f32 v[222:223], v[222:223], 1.0 op_sel_hi:[1,0]
	v_rcp_f32_e32 v216, v216
	v_rcp_f32_e32 v217, v217
	v_rcp_f32_e32 v218, v218
	v_rcp_f32_e32 v219, v219
	v_rcp_f32_e32 v220, v220
	v_rcp_f32_e32 v221, v221
	v_rcp_f32_e32 v222, v222
	v_rcp_f32_e32 v223, v223
	v_pk_mul_f32 v[216:217], v[216:217], v[224:225]
	v_pk_mul_f32 v[218:219], v[218:219], v[226:227]
	v_pk_mul_f32 v[220:221], v[220:221], v[228:229]
	v_pk_mul_f32 v[222:223], v[222:223], v[230:231]
	v_cvt_pk_f16_f32 v168, v216, v217
	v_cvt_pk_f16_f32 v169, v218, v219
	v_cvt_pk_f16_f32 v170, v220, v221
	v_cvt_pk_f16_f32 v171, v222, v223
	v_pk_fma_f32 v[102:103], v[102:103], v[176:177], v[42:43] op_sel_hi:[1,0,1]
	v_pk_fma_f32 v[104:105], v[104:105], v[176:177], v[44:45] op_sel_hi:[1,0,1]
	v_pk_fma_f32 v[98:99], v[98:99], v[176:177], v[46:47] op_sel_hi:[1,0,1]
	v_pk_fma_f32 v[100:101], v[100:101], v[176:177], v[48:49] op_sel_hi:[1,0,1]
	v_pk_mul_f32 v[216:217], v[102:103], s[90:91] op_sel_hi:[1,0]
	v_pk_mul_f32 v[218:219], v[104:105], s[90:91] op_sel_hi:[1,0]
	v_pk_mul_f32 v[220:221], v[98:99], s[90:91] op_sel_hi:[1,0]
	v_pk_mul_f32 v[222:223], v[100:101], s[90:91] op_sel_hi:[1,0]
	v_exp_f32_e32 v216, v216
	v_exp_f32_e32 v217, v217
	v_exp_f32_e32 v218, v218
	v_exp_f32_e32 v219, v219
	v_exp_f32_e32 v220, v220
	v_exp_f32_e32 v221, v221
	v_exp_f32_e32 v222, v222
	v_exp_f32_e32 v223, v223
	v_pk_add_f32 v[216:217], v[216:217], 1.0 op_sel_hi:[1,0]
	v_pk_add_f32 v[218:219], v[218:219], 1.0 op_sel_hi:[1,0]
	v_pk_add_f32 v[220:221], v[220:221], 1.0 op_sel_hi:[1,0]
	v_pk_add_f32 v[222:223], v[222:223], 1.0 op_sel_hi:[1,0]
	v_rcp_f32_e32 v216, v216
	v_rcp_f32_e32 v217, v217
	v_rcp_f32_e32 v218, v218
	v_rcp_f32_e32 v219, v219
	v_rcp_f32_e32 v220, v220
	v_rcp_f32_e32 v221, v221
	v_rcp_f32_e32 v222, v222
	v_rcp_f32_e32 v223, v223
	v_pk_mul_f32 v[216:217], v[216:217], v[232:233]
	v_pk_mul_f32 v[218:219], v[218:219], v[234:235]
	v_pk_mul_f32 v[220:221], v[220:221], v[236:237]
	v_pk_mul_f32 v[222:223], v[222:223], v[238:239]
	v_cvt_pk_f16_f32 v184, v216, v217
	v_cvt_pk_f16_f32 v185, v218, v219
	v_cvt_pk_f16_f32 v186, v220, v221
	v_cvt_pk_f16_f32 v187, v222, v223
	s_mov_b64 vcc, s[84:85]
	v_cndmask_b32_dpp v216, v184, v168, vcc quad_perm:[1,0,3,2] row_mask:0xf bank_mask:0xf
	v_cndmask_b32_dpp v217, v185, v169, vcc quad_perm:[1,0,3,2] row_mask:0xf bank_mask:0xf
	v_cndmask_b32_dpp v218, v186, v170, vcc quad_perm:[1,0,3,2] row_mask:0xf bank_mask:0xf
	v_cndmask_b32_dpp v219, v187, v171, vcc quad_perm:[1,0,3,2] row_mask:0xf bank_mask:0xf
	s_mov_b64 vcc, s[62:63]
	v_cndmask_b32_dpp v220, v168, v184, vcc quad_perm:[1,0,3,2] row_mask:0xf bank_mask:0xf
	v_cndmask_b32_dpp v221, v169, v185, vcc quad_perm:[1,0,3,2] row_mask:0xf bank_mask:0xf
	v_cndmask_b32_dpp v222, v170, v186, vcc quad_perm:[1,0,3,2] row_mask:0xf bank_mask:0xf
	v_cndmask_b32_dpp v223, v171, v187, vcc quad_perm:[1,0,3,2] row_mask:0xf bank_mask:0xf
	s_add_u32 s80, s10, 0x40000
	s_addc_u32 s81, s11, 0
	s_add_u32 s82, s10, 0x42000
	s_addc_u32 s83, s11, 0
	global_store_dwordx4 v177, v[216:219], s[80:81]
	global_store_dwordx4 v177, v[220:223], s[82:83]
	v_pk_fma_f32 v[94:95], v[94:95], v[178:179], v[26:27] op_sel_hi:[1,0,1]
	v_pk_fma_f32 v[96:97], v[96:97], v[178:179], v[28:29] op_sel_hi:[1,0,1]
	v_pk_fma_f32 v[90:91], v[90:91], v[178:179], v[30:31] op_sel_hi:[1,0,1]
	v_pk_fma_f32 v[92:93], v[92:93], v[178:179], v[32:33] op_sel_hi:[1,0,1]
	v_pk_mul_f32 v[216:217], v[94:95], s[90:91] op_sel_hi:[1,0]
	v_pk_mul_f32 v[218:219], v[96:97], s[90:91] op_sel_hi:[1,0]
	v_pk_mul_f32 v[220:221], v[90:91], s[90:91] op_sel_hi:[1,0]
	v_pk_mul_f32 v[222:223], v[92:93], s[90:91] op_sel_hi:[1,0]
	v_exp_f32_e32 v216, v216
	v_exp_f32_e32 v217, v217
	v_exp_f32_e32 v218, v218
	v_exp_f32_e32 v219, v219
	v_exp_f32_e32 v220, v220
	v_exp_f32_e32 v221, v221
	v_exp_f32_e32 v222, v222
	v_exp_f32_e32 v223, v223
	v_pk_add_f32 v[216:217], v[216:217], 1.0 op_sel_hi:[1,0]
	v_pk_add_f32 v[218:219], v[218:219], 1.0 op_sel_hi:[1,0]
	v_pk_add_f32 v[220:221], v[220:221], 1.0 op_sel_hi:[1,0]
	v_pk_add_f32 v[222:223], v[222:223], 1.0 op_sel_hi:[1,0]
	v_rcp_f32_e32 v216, v216
	v_rcp_f32_e32 v217, v217
	v_rcp_f32_e32 v218, v218
	v_rcp_f32_e32 v219, v219
	v_rcp_f32_e32 v220, v220
	v_rcp_f32_e32 v221, v221
	v_rcp_f32_e32 v222, v222
	v_rcp_f32_e32 v223, v223
	v_pk_mul_f32 v[216:217], v[216:217], v[224:225]
	v_pk_mul_f32 v[218:219], v[218:219], v[226:227]
	v_pk_mul_f32 v[220:221], v[220:221], v[228:229]
	v_pk_mul_f32 v[222:223], v[222:223], v[230:231]
	v_cvt_pk_f16_f32 v168, v216, v217
	v_cvt_pk_f16_f32 v169, v218, v219
	v_cvt_pk_f16_f32 v170, v220, v221
	v_cvt_pk_f16_f32 v171, v222, v223
	v_pk_fma_f32 v[86:87], v[86:87], v[178:179], v[42:43] op_sel_hi:[1,0,1]
	v_pk_fma_f32 v[88:89], v[88:89], v[178:179], v[44:45] op_sel_hi:[1,0,1]
	v_pk_fma_f32 v[82:83], v[82:83], v[178:179], v[46:47] op_sel_hi:[1,0,1]
	v_pk_fma_f32 v[84:85], v[84:85], v[178:179], v[48:49] op_sel_hi:[1,0,1]
	v_pk_mul_f32 v[216:217], v[86:87], s[90:91] op_sel_hi:[1,0]
	v_pk_mul_f32 v[218:219], v[88:89], s[90:91] op_sel_hi:[1,0]
	v_pk_mul_f32 v[220:221], v[82:83], s[90:91] op_sel_hi:[1,0]
	v_pk_mul_f32 v[222:223], v[84:85], s[90:91] op_sel_hi:[1,0]
	v_exp_f32_e32 v216, v216
	v_exp_f32_e32 v217, v217
	v_exp_f32_e32 v218, v218
	v_exp_f32_e32 v219, v219
	v_exp_f32_e32 v220, v220
	v_exp_f32_e32 v221, v221
	v_exp_f32_e32 v222, v222
	v_exp_f32_e32 v223, v223
	v_pk_add_f32 v[216:217], v[216:217], 1.0 op_sel_hi:[1,0]
	v_pk_add_f32 v[218:219], v[218:219], 1.0 op_sel_hi:[1,0]
	v_pk_add_f32 v[220:221], v[220:221], 1.0 op_sel_hi:[1,0]
	v_pk_add_f32 v[222:223], v[222:223], 1.0 op_sel_hi:[1,0]
	v_rcp_f32_e32 v216, v216
	v_rcp_f32_e32 v217, v217
	v_rcp_f32_e32 v218, v218
	v_rcp_f32_e32 v219, v219
	v_rcp_f32_e32 v220, v220
	v_rcp_f32_e32 v221, v221
	v_rcp_f32_e32 v222, v222
	v_rcp_f32_e32 v223, v223
	v_pk_mul_f32 v[216:217], v[216:217], v[232:233]
	v_pk_mul_f32 v[218:219], v[218:219], v[234:235]
	v_pk_mul_f32 v[220:221], v[220:221], v[236:237]
	v_pk_mul_f32 v[222:223], v[222:223], v[238:239]
	v_cvt_pk_f16_f32 v184, v216, v217
	v_cvt_pk_f16_f32 v185, v218, v219
	v_cvt_pk_f16_f32 v186, v220, v221
	v_cvt_pk_f16_f32 v187, v222, v223
	s_mov_b64 vcc, s[84:85]
	v_cndmask_b32_dpp v216, v184, v168, vcc quad_perm:[1,0,3,2] row_mask:0xf bank_mask:0xf
	v_cndmask_b32_dpp v217, v185, v169, vcc quad_perm:[1,0,3,2] row_mask:0xf bank_mask:0xf
	v_cndmask_b32_dpp v218, v186, v170, vcc quad_perm:[1,0,3,2] row_mask:0xf bank_mask:0xf
	v_cndmask_b32_dpp v219, v187, v171, vcc quad_perm:[1,0,3,2] row_mask:0xf bank_mask:0xf
	s_mov_b64 vcc, s[62:63]
	v_cndmask_b32_dpp v220, v168, v184, vcc quad_perm:[1,0,3,2] row_mask:0xf bank_mask:0xf
	v_cndmask_b32_dpp v221, v169, v185, vcc quad_perm:[1,0,3,2] row_mask:0xf bank_mask:0xf
	v_cndmask_b32_dpp v222, v170, v186, vcc quad_perm:[1,0,3,2] row_mask:0xf bank_mask:0xf
	v_cndmask_b32_dpp v223, v171, v187, vcc quad_perm:[1,0,3,2] row_mask:0xf bank_mask:0xf
	s_add_u32 s80, s10, 0x60000
	s_addc_u32 s81, s11, 0
	s_add_u32 s82, s10, 0x62000
	s_addc_u32 s83, s11, 0
	global_store_dwordx4 v177, v[216:219], s[80:81]
	global_store_dwordx4 v177, v[220:223], s[82:83]
	v_pk_fma_f32 v[78:79], v[78:79], v[180:181], v[26:27] op_sel_hi:[1,0,1]
	v_pk_fma_f32 v[80:81], v[80:81], v[180:181], v[28:29] op_sel_hi:[1,0,1]
	v_pk_fma_f32 v[74:75], v[74:75], v[180:181], v[30:31] op_sel_hi:[1,0,1]
	v_pk_fma_f32 v[76:77], v[76:77], v[180:181], v[32:33] op_sel_hi:[1,0,1]
	v_pk_mul_f32 v[216:217], v[78:79], s[90:91] op_sel_hi:[1,0]
	v_pk_mul_f32 v[218:219], v[80:81], s[90:91] op_sel_hi:[1,0]
	v_pk_mul_f32 v[220:221], v[74:75], s[90:91] op_sel_hi:[1,0]
	v_pk_mul_f32 v[222:223], v[76:77], s[90:91] op_sel_hi:[1,0]
	v_exp_f32_e32 v216, v216
	v_exp_f32_e32 v217, v217
	v_exp_f32_e32 v218, v218
	v_exp_f32_e32 v219, v219
	v_exp_f32_e32 v220, v220
	v_exp_f32_e32 v221, v221
	v_exp_f32_e32 v222, v222
	v_exp_f32_e32 v223, v223
	v_pk_add_f32 v[216:217], v[216:217], 1.0 op_sel_hi:[1,0]
	v_pk_add_f32 v[218:219], v[218:219], 1.0 op_sel_hi:[1,0]
	v_pk_add_f32 v[220:221], v[220:221], 1.0 op_sel_hi:[1,0]
	v_pk_add_f32 v[222:223], v[222:223], 1.0 op_sel_hi:[1,0]
	v_rcp_f32_e32 v216, v216
	v_rcp_f32_e32 v217, v217
	v_rcp_f32_e32 v218, v218
	v_rcp_f32_e32 v219, v219
	v_rcp_f32_e32 v220, v220
	v_rcp_f32_e32 v221, v221
	v_rcp_f32_e32 v222, v222
	v_rcp_f32_e32 v223, v223
	v_pk_mul_f32 v[216:217], v[216:217], v[224:225]
	v_pk_mul_f32 v[218:219], v[218:219], v[226:227]
	v_pk_mul_f32 v[220:221], v[220:221], v[228:229]
	v_pk_mul_f32 v[222:223], v[222:223], v[230:231]
	v_cvt_pk_f16_f32 v168, v216, v217
	v_cvt_pk_f16_f32 v169, v218, v219
	v_cvt_pk_f16_f32 v170, v220, v221
	v_cvt_pk_f16_f32 v171, v222, v223
	v_pk_fma_f32 v[70:71], v[70:71], v[180:181], v[42:43] op_sel_hi:[1,0,1]
	v_pk_fma_f32 v[72:73], v[72:73], v[180:181], v[44:45] op_sel_hi:[1,0,1]
	v_pk_fma_f32 v[66:67], v[66:67], v[180:181], v[46:47] op_sel_hi:[1,0,1]
	v_pk_fma_f32 v[68:69], v[68:69], v[180:181], v[48:49] op_sel_hi:[1,0,1]
	v_pk_mul_f32 v[216:217], v[70:71], s[90:91] op_sel_hi:[1,0]
	v_pk_mul_f32 v[218:219], v[72:73], s[90:91] op_sel_hi:[1,0]
	v_pk_mul_f32 v[220:221], v[66:67], s[90:91] op_sel_hi:[1,0]
	v_pk_mul_f32 v[222:223], v[68:69], s[90:91] op_sel_hi:[1,0]
	v_exp_f32_e32 v216, v216
	v_exp_f32_e32 v217, v217
	v_exp_f32_e32 v218, v218
	v_exp_f32_e32 v219, v219
	v_exp_f32_e32 v220, v220
	v_exp_f32_e32 v221, v221
	v_exp_f32_e32 v222, v222
	v_exp_f32_e32 v223, v223
	v_pk_add_f32 v[216:217], v[216:217], 1.0 op_sel_hi:[1,0]
	v_pk_add_f32 v[218:219], v[218:219], 1.0 op_sel_hi:[1,0]
	v_pk_add_f32 v[220:221], v[220:221], 1.0 op_sel_hi:[1,0]
	v_pk_add_f32 v[222:223], v[222:223], 1.0 op_sel_hi:[1,0]
	v_rcp_f32_e32 v216, v216
	v_rcp_f32_e32 v217, v217
	v_rcp_f32_e32 v218, v218
	v_rcp_f32_e32 v219, v219
	v_rcp_f32_e32 v220, v220
	v_rcp_f32_e32 v221, v221
	v_rcp_f32_e32 v222, v222
	v_rcp_f32_e32 v223, v223
	v_pk_mul_f32 v[216:217], v[216:217], v[232:233]
	v_pk_mul_f32 v[218:219], v[218:219], v[234:235]
	v_pk_mul_f32 v[220:221], v[220:221], v[236:237]
	v_pk_mul_f32 v[222:223], v[222:223], v[238:239]
	v_cvt_pk_f16_f32 v184, v216, v217
	v_cvt_pk_f16_f32 v185, v218, v219
	v_cvt_pk_f16_f32 v186, v220, v221
	v_cvt_pk_f16_f32 v187, v222, v223
	s_mov_b64 vcc, s[84:85]
	v_cndmask_b32_dpp v216, v184, v168, vcc quad_perm:[1,0,3,2] row_mask:0xf bank_mask:0xf
	v_cndmask_b32_dpp v217, v185, v169, vcc quad_perm:[1,0,3,2] row_mask:0xf bank_mask:0xf
	v_cndmask_b32_dpp v218, v186, v170, vcc quad_perm:[1,0,3,2] row_mask:0xf bank_mask:0xf
	v_cndmask_b32_dpp v219, v187, v171, vcc quad_perm:[1,0,3,2] row_mask:0xf bank_mask:0xf
	s_mov_b64 vcc, s[62:63]
	v_cndmask_b32_dpp v220, v168, v184, vcc quad_perm:[1,0,3,2] row_mask:0xf bank_mask:0xf
	v_cndmask_b32_dpp v221, v169, v185, vcc quad_perm:[1,0,3,2] row_mask:0xf bank_mask:0xf
	v_cndmask_b32_dpp v222, v170, v186, vcc quad_perm:[1,0,3,2] row_mask:0xf bank_mask:0xf
	v_cndmask_b32_dpp v223, v171, v187, vcc quad_perm:[1,0,3,2] row_mask:0xf bank_mask:0xf
	s_add_u32 s80, s10, 0x100000
	s_addc_u32 s81, s11, 0
	s_add_u32 s82, s10, 0x102000
	s_addc_u32 s83, s11, 0
	global_store_dwordx4 v177, v[216:219], s[80:81]
	global_store_dwordx4 v177, v[220:223], s[82:83]
	v_pk_fma_f32 v[62:63], v[62:63], v[182:183], v[26:27] op_sel_hi:[1,0,1]
	v_pk_fma_f32 v[64:65], v[64:65], v[182:183], v[28:29] op_sel_hi:[1,0,1]
	v_pk_fma_f32 v[58:59], v[58:59], v[182:183], v[30:31] op_sel_hi:[1,0,1]
	v_pk_fma_f32 v[60:61], v[60:61], v[182:183], v[32:33] op_sel_hi:[1,0,1]
	v_pk_mul_f32 v[216:217], v[62:63], s[90:91] op_sel_hi:[1,0]
	v_pk_mul_f32 v[218:219], v[64:65], s[90:91] op_sel_hi:[1,0]
	v_pk_mul_f32 v[220:221], v[58:59], s[90:91] op_sel_hi:[1,0]
	v_pk_mul_f32 v[222:223], v[60:61], s[90:91] op_sel_hi:[1,0]
	v_exp_f32_e32 v216, v216
	v_exp_f32_e32 v217, v217
	v_exp_f32_e32 v218, v218
	v_exp_f32_e32 v219, v219
	v_exp_f32_e32 v220, v220
	v_exp_f32_e32 v221, v221
	v_exp_f32_e32 v222, v222
	v_exp_f32_e32 v223, v223
	v_pk_add_f32 v[216:217], v[216:217], 1.0 op_sel_hi:[1,0]
	v_pk_add_f32 v[218:219], v[218:219], 1.0 op_sel_hi:[1,0]
	v_pk_add_f32 v[220:221], v[220:221], 1.0 op_sel_hi:[1,0]
	v_pk_add_f32 v[222:223], v[222:223], 1.0 op_sel_hi:[1,0]
	v_rcp_f32_e32 v216, v216
	v_rcp_f32_e32 v217, v217
	v_rcp_f32_e32 v218, v218
	v_rcp_f32_e32 v219, v219
	v_rcp_f32_e32 v220, v220
	v_rcp_f32_e32 v221, v221
	v_rcp_f32_e32 v222, v222
	v_rcp_f32_e32 v223, v223
	v_pk_mul_f32 v[216:217], v[216:217], v[224:225]
	v_pk_mul_f32 v[218:219], v[218:219], v[226:227]
	v_pk_mul_f32 v[220:221], v[220:221], v[228:229]
	v_pk_mul_f32 v[222:223], v[222:223], v[230:231]
	v_cvt_pk_f16_f32 v168, v216, v217
	v_cvt_pk_f16_f32 v169, v218, v219
	v_cvt_pk_f16_f32 v170, v220, v221
	v_cvt_pk_f16_f32 v171, v222, v223
	v_pk_fma_f32 v[54:55], v[54:55], v[182:183], v[42:43] op_sel_hi:[1,0,1]
	v_pk_fma_f32 v[56:57], v[56:57], v[182:183], v[44:45] op_sel_hi:[1,0,1]
	v_pk_fma_f32 v[50:51], v[50:51], v[182:183], v[46:47] op_sel_hi:[1,0,1]
	v_pk_fma_f32 v[52:53], v[52:53], v[182:183], v[48:49] op_sel_hi:[1,0,1]
	v_pk_mul_f32 v[216:217], v[54:55], s[90:91] op_sel_hi:[1,0]
	v_pk_mul_f32 v[218:219], v[56:57], s[90:91] op_sel_hi:[1,0]
	v_pk_mul_f32 v[220:221], v[50:51], s[90:91] op_sel_hi:[1,0]
	v_pk_mul_f32 v[222:223], v[52:53], s[90:91] op_sel_hi:[1,0]
	v_exp_f32_e32 v216, v216
	v_exp_f32_e32 v217, v217
	v_exp_f32_e32 v218, v218
	v_exp_f32_e32 v219, v219
	v_exp_f32_e32 v220, v220
	v_exp_f32_e32 v221, v221
	v_exp_f32_e32 v222, v222
	v_exp_f32_e32 v223, v223
	v_pk_add_f32 v[216:217], v[216:217], 1.0 op_sel_hi:[1,0]
	v_pk_add_f32 v[218:219], v[218:219], 1.0 op_sel_hi:[1,0]
	v_pk_add_f32 v[220:221], v[220:221], 1.0 op_sel_hi:[1,0]
	v_pk_add_f32 v[222:223], v[222:223], 1.0 op_sel_hi:[1,0]
	v_rcp_f32_e32 v216, v216
	v_rcp_f32_e32 v217, v217
	v_rcp_f32_e32 v218, v218
	v_rcp_f32_e32 v219, v219
	v_rcp_f32_e32 v220, v220
	v_rcp_f32_e32 v221, v221
	v_rcp_f32_e32 v222, v222
	v_rcp_f32_e32 v223, v223
	v_pk_mul_f32 v[216:217], v[216:217], v[232:233]
	v_pk_mul_f32 v[218:219], v[218:219], v[234:235]
	v_pk_mul_f32 v[220:221], v[220:221], v[236:237]
	v_pk_mul_f32 v[222:223], v[222:223], v[238:239]
	v_cvt_pk_f16_f32 v184, v216, v217
	v_cvt_pk_f16_f32 v185, v218, v219
	v_cvt_pk_f16_f32 v186, v220, v221
	v_cvt_pk_f16_f32 v187, v222, v223
	s_mov_b64 vcc, s[84:85]
	v_cndmask_b32_dpp v216, v184, v168, vcc quad_perm:[1,0,3,2] row_mask:0xf bank_mask:0xf
	v_cndmask_b32_dpp v217, v185, v169, vcc quad_perm:[1,0,3,2] row_mask:0xf bank_mask:0xf
	v_cndmask_b32_dpp v218, v186, v170, vcc quad_perm:[1,0,3,2] row_mask:0xf bank_mask:0xf
	v_cndmask_b32_dpp v219, v187, v171, vcc quad_perm:[1,0,3,2] row_mask:0xf bank_mask:0xf
	s_mov_b64 vcc, s[62:63]
	v_cndmask_b32_dpp v220, v168, v184, vcc quad_perm:[1,0,3,2] row_mask:0xf bank_mask:0xf
	v_cndmask_b32_dpp v221, v169, v185, vcc quad_perm:[1,0,3,2] row_mask:0xf bank_mask:0xf
	v_cndmask_b32_dpp v222, v170, v186, vcc quad_perm:[1,0,3,2] row_mask:0xf bank_mask:0xf
	v_cndmask_b32_dpp v223, v171, v187, vcc quad_perm:[1,0,3,2] row_mask:0xf bank_mask:0xf
	s_add_u32 s80, s10, 0x120000
	s_addc_u32 s81, s11, 0
	s_add_u32 s82, s10, 0x122000
	s_addc_u32 s83, s11, 0
	global_store_dwordx4 v177, v[216:219], s[80:81]
	global_store_dwordx4 v177, v[220:223], s[82:83]
	v_pk_fma_f32 v[38:39], v[38:39], v[188:189], v[26:27] op_sel_hi:[1,0,1]
	v_pk_fma_f32 v[40:41], v[40:41], v[188:189], v[28:29] op_sel_hi:[1,0,1]
	v_pk_fma_f32 v[34:35], v[34:35], v[188:189], v[30:31] op_sel_hi:[1,0,1]
	v_pk_fma_f32 v[36:37], v[36:37], v[188:189], v[32:33] op_sel_hi:[1,0,1]
	v_pk_mul_f32 v[216:217], v[38:39], s[90:91] op_sel_hi:[1,0]
	v_pk_mul_f32 v[218:219], v[40:41], s[90:91] op_sel_hi:[1,0]
	v_pk_mul_f32 v[220:221], v[34:35], s[90:91] op_sel_hi:[1,0]
	v_pk_mul_f32 v[222:223], v[36:37], s[90:91] op_sel_hi:[1,0]
	v_exp_f32_e32 v216, v216
	v_exp_f32_e32 v217, v217
	v_exp_f32_e32 v218, v218
	v_exp_f32_e32 v219, v219
	v_exp_f32_e32 v220, v220
	v_exp_f32_e32 v221, v221
	v_exp_f32_e32 v222, v222
	v_exp_f32_e32 v223, v223
	v_pk_add_f32 v[216:217], v[216:217], 1.0 op_sel_hi:[1,0]
	v_pk_add_f32 v[218:219], v[218:219], 1.0 op_sel_hi:[1,0]
	v_pk_add_f32 v[220:221], v[220:221], 1.0 op_sel_hi:[1,0]
	v_pk_add_f32 v[222:223], v[222:223], 1.0 op_sel_hi:[1,0]
	v_rcp_f32_e32 v216, v216
	v_rcp_f32_e32 v217, v217
	v_rcp_f32_e32 v218, v218
	v_rcp_f32_e32 v219, v219
	v_rcp_f32_e32 v220, v220
	v_rcp_f32_e32 v221, v221
	v_rcp_f32_e32 v222, v222
	v_rcp_f32_e32 v223, v223
	v_pk_mul_f32 v[216:217], v[216:217], v[224:225]
	v_pk_mul_f32 v[218:219], v[218:219], v[226:227]
	v_pk_mul_f32 v[220:221], v[220:221], v[228:229]
	v_pk_mul_f32 v[222:223], v[222:223], v[230:231]
	v_cvt_pk_f16_f32 v168, v216, v217
	v_cvt_pk_f16_f32 v169, v218, v219
	v_cvt_pk_f16_f32 v170, v220, v221
	v_cvt_pk_f16_f32 v171, v222, v223
	v_pk_fma_f32 v[22:23], v[22:23], v[188:189], v[42:43] op_sel_hi:[1,0,1]
	v_pk_fma_f32 v[24:25], v[24:25], v[188:189], v[44:45] op_sel_hi:[1,0,1]
	v_pk_fma_f32 v[18:19], v[18:19], v[188:189], v[46:47] op_sel_hi:[1,0,1]
	v_pk_fma_f32 v[20:21], v[20:21], v[188:189], v[48:49] op_sel_hi:[1,0,1]
	v_pk_mul_f32 v[216:217], v[22:23], s[90:91] op_sel_hi:[1,0]
	v_pk_mul_f32 v[218:219], v[24:25], s[90:91] op_sel_hi:[1,0]
	v_pk_mul_f32 v[220:221], v[18:19], s[90:91] op_sel_hi:[1,0]
	v_pk_mul_f32 v[222:223], v[20:21], s[90:91] op_sel_hi:[1,0]
	v_exp_f32_e32 v216, v216
	v_exp_f32_e32 v217, v217
	v_exp_f32_e32 v218, v218
	v_exp_f32_e32 v219, v219
	v_exp_f32_e32 v220, v220
	v_exp_f32_e32 v221, v221
	v_exp_f32_e32 v222, v222
	v_exp_f32_e32 v223, v223
	v_pk_add_f32 v[216:217], v[216:217], 1.0 op_sel_hi:[1,0]
	v_pk_add_f32 v[218:219], v[218:219], 1.0 op_sel_hi:[1,0]
	v_pk_add_f32 v[220:221], v[220:221], 1.0 op_sel_hi:[1,0]
	v_pk_add_f32 v[222:223], v[222:223], 1.0 op_sel_hi:[1,0]
	v_rcp_f32_e32 v216, v216
	v_rcp_f32_e32 v217, v217
	v_rcp_f32_e32 v218, v218
	v_rcp_f32_e32 v219, v219
	v_rcp_f32_e32 v220, v220
	v_rcp_f32_e32 v221, v221
	v_rcp_f32_e32 v222, v222
	v_rcp_f32_e32 v223, v223
	v_pk_mul_f32 v[216:217], v[216:217], v[232:233]
	v_pk_mul_f32 v[218:219], v[218:219], v[234:235]
	v_pk_mul_f32 v[220:221], v[220:221], v[236:237]
	v_pk_mul_f32 v[222:223], v[222:223], v[238:239]
	v_cvt_pk_f16_f32 v184, v216, v217
	v_cvt_pk_f16_f32 v185, v218, v219
	v_cvt_pk_f16_f32 v186, v220, v221
	v_cvt_pk_f16_f32 v187, v222, v223
	s_mov_b64 vcc, s[84:85]
	v_cndmask_b32_dpp v216, v184, v168, vcc quad_perm:[1,0,3,2] row_mask:0xf bank_mask:0xf
	v_cndmask_b32_dpp v217, v185, v169, vcc quad_perm:[1,0,3,2] row_mask:0xf bank_mask:0xf
	v_cndmask_b32_dpp v218, v186, v170, vcc quad_perm:[1,0,3,2] row_mask:0xf bank_mask:0xf
	v_cndmask_b32_dpp v219, v187, v171, vcc quad_perm:[1,0,3,2] row_mask:0xf bank_mask:0xf
	s_mov_b64 vcc, s[62:63]
	v_cndmask_b32_dpp v220, v168, v184, vcc quad_perm:[1,0,3,2] row_mask:0xf bank_mask:0xf
	v_cndmask_b32_dpp v221, v169, v185, vcc quad_perm:[1,0,3,2] row_mask:0xf bank_mask:0xf
	v_cndmask_b32_dpp v222, v170, v186, vcc quad_perm:[1,0,3,2] row_mask:0xf bank_mask:0xf
	v_cndmask_b32_dpp v223, v171, v187, vcc quad_perm:[1,0,3,2] row_mask:0xf bank_mask:0xf
	s_add_u32 s80, s10, 0x140000
	s_addc_u32 s81, s11, 0
	s_add_u32 s82, s10, 0x142000
	s_addc_u32 s83, s11, 0
	global_store_dwordx4 v177, v[216:219], s[80:81]
	global_store_dwordx4 v177, v[220:223], s[82:83]
	v_pk_fma_f32 v[14:15], v[14:15], v[240:241], v[26:27] op_sel_hi:[1,0,1]
	v_pk_fma_f32 v[16:17], v[16:17], v[240:241], v[28:29] op_sel_hi:[1,0,1]
	v_pk_fma_f32 v[10:11], v[10:11], v[240:241], v[30:31] op_sel_hi:[1,0,1]
	v_pk_fma_f32 v[12:13], v[12:13], v[240:241], v[32:33] op_sel_hi:[1,0,1]
	v_pk_mul_f32 v[216:217], v[14:15], s[90:91] op_sel_hi:[1,0]
	v_pk_mul_f32 v[218:219], v[16:17], s[90:91] op_sel_hi:[1,0]
	v_pk_mul_f32 v[220:221], v[10:11], s[90:91] op_sel_hi:[1,0]
	v_pk_mul_f32 v[222:223], v[12:13], s[90:91] op_sel_hi:[1,0]
	v_exp_f32_e32 v216, v216
	v_exp_f32_e32 v217, v217
	v_exp_f32_e32 v218, v218
	v_exp_f32_e32 v219, v219
	v_exp_f32_e32 v220, v220
	v_exp_f32_e32 v221, v221
	v_exp_f32_e32 v222, v222
	v_exp_f32_e32 v223, v223
	v_pk_add_f32 v[216:217], v[216:217], 1.0 op_sel_hi:[1,0]
	v_pk_add_f32 v[218:219], v[218:219], 1.0 op_sel_hi:[1,0]
	v_pk_add_f32 v[220:221], v[220:221], 1.0 op_sel_hi:[1,0]
	v_pk_add_f32 v[222:223], v[222:223], 1.0 op_sel_hi:[1,0]
	v_rcp_f32_e32 v216, v216
	v_rcp_f32_e32 v217, v217
	v_rcp_f32_e32 v218, v218
	v_rcp_f32_e32 v219, v219
	v_rcp_f32_e32 v220, v220
	v_rcp_f32_e32 v221, v221
	v_rcp_f32_e32 v222, v222
	v_rcp_f32_e32 v223, v223
	v_pk_mul_f32 v[216:217], v[216:217], v[224:225]
	v_pk_mul_f32 v[218:219], v[218:219], v[226:227]
	v_pk_mul_f32 v[220:221], v[220:221], v[228:229]
	v_pk_mul_f32 v[222:223], v[222:223], v[230:231]
	v_cvt_pk_f16_f32 v168, v216, v217
	v_cvt_pk_f16_f32 v169, v218, v219
	v_cvt_pk_f16_f32 v170, v220, v221
	v_cvt_pk_f16_f32 v171, v222, v223
	v_pk_fma_f32 v[6:7], v[6:7], v[240:241], v[42:43] op_sel_hi:[1,0,1]
	v_pk_fma_f32 v[8:9], v[8:9], v[240:241], v[44:45] op_sel_hi:[1,0,1]
	v_pk_fma_f32 v[2:3], v[2:3], v[240:241], v[46:47] op_sel_hi:[1,0,1]
	v_pk_fma_f32 v[4:5], v[4:5], v[240:241], v[48:49] op_sel_hi:[1,0,1]
	v_pk_mul_f32 v[216:217], v[6:7], s[90:91] op_sel_hi:[1,0]
	v_pk_mul_f32 v[218:219], v[8:9], s[90:91] op_sel_hi:[1,0]
	v_pk_mul_f32 v[220:221], v[2:3], s[90:91] op_sel_hi:[1,0]
	v_pk_mul_f32 v[222:223], v[4:5], s[90:91] op_sel_hi:[1,0]
	v_exp_f32_e32 v216, v216
	v_exp_f32_e32 v217, v217
	v_exp_f32_e32 v218, v218
	v_exp_f32_e32 v219, v219
	v_exp_f32_e32 v220, v220
	v_exp_f32_e32 v221, v221
	v_exp_f32_e32 v222, v222
	v_exp_f32_e32 v223, v223
	v_pk_add_f32 v[216:217], v[216:217], 1.0 op_sel_hi:[1,0]
	v_pk_add_f32 v[218:219], v[218:219], 1.0 op_sel_hi:[1,0]
	v_pk_add_f32 v[220:221], v[220:221], 1.0 op_sel_hi:[1,0]
	v_pk_add_f32 v[222:223], v[222:223], 1.0 op_sel_hi:[1,0]
	v_rcp_f32_e32 v216, v216
	v_rcp_f32_e32 v217, v217
	v_rcp_f32_e32 v218, v218
	v_rcp_f32_e32 v219, v219
	v_rcp_f32_e32 v220, v220
	v_rcp_f32_e32 v221, v221
	v_rcp_f32_e32 v222, v222
	v_rcp_f32_e32 v223, v223
	v_pk_mul_f32 v[216:217], v[216:217], v[232:233]
	v_pk_mul_f32 v[218:219], v[218:219], v[234:235]
	v_pk_mul_f32 v[220:221], v[220:221], v[236:237]
	v_pk_mul_f32 v[222:223], v[222:223], v[238:239]
	v_cvt_pk_f16_f32 v184, v216, v217
	v_cvt_pk_f16_f32 v185, v218, v219
	v_cvt_pk_f16_f32 v186, v220, v221
	v_cvt_pk_f16_f32 v187, v222, v223
	s_mov_b64 vcc, s[84:85]
	v_cndmask_b32_dpp v216, v184, v168, vcc quad_perm:[1,0,3,2] row_mask:0xf bank_mask:0xf
	v_cndmask_b32_dpp v217, v185, v169, vcc quad_perm:[1,0,3,2] row_mask:0xf bank_mask:0xf
	v_cndmask_b32_dpp v218, v186, v170, vcc quad_perm:[1,0,3,2] row_mask:0xf bank_mask:0xf
	v_cndmask_b32_dpp v219, v187, v171, vcc quad_perm:[1,0,3,2] row_mask:0xf bank_mask:0xf
	s_mov_b64 vcc, s[62:63]
	v_cndmask_b32_dpp v220, v168, v184, vcc quad_perm:[1,0,3,2] row_mask:0xf bank_mask:0xf
	v_cndmask_b32_dpp v221, v169, v185, vcc quad_perm:[1,0,3,2] row_mask:0xf bank_mask:0xf
	v_cndmask_b32_dpp v222, v170, v186, vcc quad_perm:[1,0,3,2] row_mask:0xf bank_mask:0xf
	v_cndmask_b32_dpp v223, v171, v187, vcc quad_perm:[1,0,3,2] row_mask:0xf bank_mask:0xf
	s_add_u32 s80, s10, 0x160000
	s_addc_u32 s81, s11, 0
	s_add_u32 s82, s10, 0x162000
	s_addc_u32 s83, s11, 0
	global_store_dwordx4 v177, v[216:219], s[80:81]
	global_store_dwordx4 v177, v[220:223], s[82:83]

.LBB0_1394:
	s_lshl_b32 s26, s52, 11
	s_add_i32 s26, s26, 0x20400
	s_lshl_b32 s27, s40, 2
	s_add_i32 s27, s26, s27
	v_lshl_add_u32 v130, v180, 2, s27
	ds_read_b32 v134, v130 offset:0
	ds_read_b32 v136, v130 offset:64
	ds_read_b32 v138, v130 offset:128
	ds_read_b32 v140, v130 offset:192
	ds_read_b32 v142, v130 offset:512
	ds_read_b32 v144, v130 offset:576
	ds_read_b32 v168, v130 offset:640
	ds_read_b32 v170, v130 offset:704
	s_lshl_b32 s27, s41, 2
	s_add_i32 s27, s26, s27
	v_lshl_add_u32 v130, v182, 2, s27
	ds_read_b128 v[172:175], v130 offset:1024
	ds_read_b128 v[176:179], v130 offset:1040
	ds_read_b128 v[186:189], v130 offset:1536
	ds_read_b128 v[190:193], v130 offset:1552
	s_mov_b32 s62, 0xaaaaaaaa
	s_mov_b32 s63, 0xaaaaaaaa
	s_mov_b32 s66, 0x55555555
	s_mov_b32 s67, 0x55555555
	v_and_b32_e32 v132, 1, v180
	v_lshl_or_b32 v131, s41, 1, v182
	v_lshl_or_b32 v131, s48, 8, v131
	v_lshl_add_u32 v131, v132, 5, v131
	v_lshl_add_u32 v130, s49, 8, v181
	v_sub_u32_e32 v130, v130, v132
	v_lshlrev_b32_e32 v130, 13, v130
	v_lshl_add_u32 v131, v131, 1, v130
	s_waitcnt lgkmcnt(0)
	v_pk_fma_f32 v[126:127], v[126:127], v[134:135], v[172:173] op_sel_hi:[1,0,1]
	v_pk_fma_f32 v[128:129], v[128:129], v[134:135], v[174:175] op_sel_hi:[1,0,1]
	v_pk_fma_f32 v[122:123], v[122:123], v[134:135], v[176:177] op_sel_hi:[1,0,1]
	v_pk_fma_f32 v[124:125], v[124:125], v[134:135], v[178:179] op_sel_hi:[1,0,1]
	v_max_f32_e32 v126, 0, v126
	v_max_f32_e32 v127, 0, v127
	v_max_f32_e32 v128, 0, v128
	v_max_f32_e32 v129, 0, v129
	v_max_f32_e32 v122, 0, v122
	v_max_f32_e32 v123, 0, v123
	v_max_f32_e32 v124, 0, v124
	v_max_f32_e32 v125, 0, v125
	v_pk_mul_f32 v[126:127], v[126:127], v[126:127]
	v_pk_mul_f32 v[128:129], v[128:129], v[128:129]
	v_pk_mul_f32 v[122:123], v[122:123], v[122:123]
	v_pk_mul_f32 v[124:125], v[124:125], v[124:125]
	v_cvt_pk_bf16_f32 v212, v126, v127
	v_cvt_pk_bf16_f32 v213, v128, v129
	v_cvt_pk_bf16_f32 v214, v122, v123
	v_cvt_pk_bf16_f32 v215, v124, v125
	v_pk_fma_f32 v[118:119], v[118:119], v[134:135], v[186:187] op_sel_hi:[1,0,1]
	v_pk_fma_f32 v[120:121], v[120:121], v[134:135], v[188:189] op_sel_hi:[1,0,1]
	v_pk_fma_f32 v[114:115], v[114:115], v[134:135], v[190:191] op_sel_hi:[1,0,1]
	v_pk_fma_f32 v[116:117], v[116:117], v[134:135], v[192:193] op_sel_hi:[1,0,1]
	v_max_f32_e32 v118, 0, v118
	v_max_f32_e32 v119, 0, v119
	v_max_f32_e32 v120, 0, v120
	v_max_f32_e32 v121, 0, v121
	v_max_f32_e32 v114, 0, v114
	v_max_f32_e32 v115, 0, v115
	v_max_f32_e32 v116, 0, v116
	v_max_f32_e32 v117, 0, v117
	v_pk_mul_f32 v[118:119], v[118:119], v[118:119]
	v_pk_mul_f32 v[120:121], v[120:121], v[120:121]
	v_pk_mul_f32 v[114:115], v[114:115], v[114:115]
	v_pk_mul_f32 v[116:117], v[116:117], v[116:117]
	v_cvt_pk_bf16_f32 v216, v118, v119
	v_cvt_pk_bf16_f32 v217, v120, v121
	v_cvt_pk_bf16_f32 v218, v114, v115
	v_cvt_pk_bf16_f32 v219, v116, v117
	s_mov_b64 vcc, s[66:67]
	v_cndmask_b32_dpp v220, v216, v212, vcc quad_perm:[1,0,3,2] row_mask:0xf bank_mask:0xf
	v_cndmask_b32_dpp v221, v217, v213, vcc quad_perm:[1,0,3,2] row_mask:0xf bank_mask:0xf
	v_cndmask_b32_dpp v222, v218, v214, vcc quad_perm:[1,0,3,2] row_mask:0xf bank_mask:0xf
	v_cndmask_b32_dpp v223, v219, v215, vcc quad_perm:[1,0,3,2] row_mask:0xf bank_mask:0xf
	s_mov_b64 vcc, s[62:63]
	v_cndmask_b32_dpp v224, v212, v216, vcc quad_perm:[1,0,3,2] row_mask:0xf bank_mask:0xf
	v_cndmask_b32_dpp v225, v213, v217, vcc quad_perm:[1,0,3,2] row_mask:0xf bank_mask:0xf
	v_cndmask_b32_dpp v226, v214, v218, vcc quad_perm:[1,0,3,2] row_mask:0xf bank_mask:0xf
	v_cndmask_b32_dpp v227, v215, v219, vcc quad_perm:[1,0,3,2] row_mask:0xf bank_mask:0xf
	s_add_u32 s80, s10, 0x0
	s_addc_u32 s81, s11, 0
	s_add_u32 s82, s10, 0x2000
	s_addc_u32 s83, s11, 0
	global_store_dwordx4 v131, v[220:223], s[80:81]
	global_store_dwordx4 v131, v[224:227], s[82:83]
	v_pk_fma_f32 v[110:111], v[110:111], v[136:137], v[172:173] op_sel_hi:[1,0,1]
	v_pk_fma_f32 v[112:113], v[112:113], v[136:137], v[174:175] op_sel_hi:[1,0,1]
	v_pk_fma_f32 v[106:107], v[106:107], v[136:137], v[176:177] op_sel_hi:[1,0,1]
	v_pk_fma_f32 v[108:109], v[108:109], v[136:137], v[178:179] op_sel_hi:[1,0,1]
	v_max_f32_e32 v110, 0, v110
	v_max_f32_e32 v111, 0, v111
	v_max_f32_e32 v112, 0, v112
	v_max_f32_e32 v113, 0, v113
	v_max_f32_e32 v106, 0, v106
	v_max_f32_e32 v107, 0, v107
	v_max_f32_e32 v108, 0, v108
	v_max_f32_e32 v109, 0, v109
	v_pk_mul_f32 v[110:111], v[110:111], v[110:111]
	v_pk_mul_f32 v[112:113], v[112:113], v[112:113]
	v_pk_mul_f32 v[106:107], v[106:107], v[106:107]
	v_pk_mul_f32 v[108:109], v[108:109], v[108:109]
	v_cvt_pk_bf16_f32 v212, v110, v111
	v_cvt_pk_bf16_f32 v213, v112, v113
	v_cvt_pk_bf16_f32 v214, v106, v107
	v_cvt_pk_bf16_f32 v215, v108, v109
	v_pk_fma_f32 v[102:103], v[102:103], v[136:137], v[186:187] op_sel_hi:[1,0,1]
	v_pk_fma_f32 v[104:105], v[104:105], v[136:137], v[188:189] op_sel_hi:[1,0,1]
	v_pk_fma_f32 v[98:99], v[98:99], v[136:137], v[190:191] op_sel_hi:[1,0,1]
	v_pk_fma_f32 v[100:101], v[100:101], v[136:137], v[192:193] op_sel_hi:[1,0,1]
	v_max_f32_e32 v102, 0, v102
	v_max_f32_e32 v103, 0, v103
	v_max_f32_e32 v104, 0, v104
	v_max_f32_e32 v105, 0, v105
	v_max_f32_e32 v98, 0, v98
	v_max_f32_e32 v99, 0, v99
	v_max_f32_e32 v100, 0, v100
	v_max_f32_e32 v101, 0, v101
	v_pk_mul_f32 v[102:103], v[102:103], v[102:103]
	v_pk_mul_f32 v[104:105], v[104:105], v[104:105]
	v_pk_mul_f32 v[98:99], v[98:99], v[98:99]
	v_pk_mul_f32 v[100:101], v[100:101], v[100:101]
	v_cvt_pk_bf16_f32 v216, v102, v103
	v_cvt_pk_bf16_f32 v217, v104, v105
	v_cvt_pk_bf16_f32 v218, v98, v99
	v_cvt_pk_bf16_f32 v219, v100, v101
	s_mov_b64 vcc, s[66:67]
	v_cndmask_b32_dpp v220, v216, v212, vcc quad_perm:[1,0,3,2] row_mask:0xf bank_mask:0xf
	v_cndmask_b32_dpp v221, v217, v213, vcc quad_perm:[1,0,3,2] row_mask:0xf bank_mask:0xf
	v_cndmask_b32_dpp v222, v218, v214, vcc quad_perm:[1,0,3,2] row_mask:0xf bank_mask:0xf
	v_cndmask_b32_dpp v223, v219, v215, vcc quad_perm:[1,0,3,2] row_mask:0xf bank_mask:0xf
	s_mov_b64 vcc, s[62:63]
	v_cndmask_b32_dpp v224, v212, v216, vcc quad_perm:[1,0,3,2] row_mask:0xf bank_mask:0xf
	v_cndmask_b32_dpp v225, v213, v217, vcc quad_perm:[1,0,3,2] row_mask:0xf bank_mask:0xf
	v_cndmask_b32_dpp v226, v214, v218, vcc quad_perm:[1,0,3,2] row_mask:0xf bank_mask:0xf
	v_cndmask_b32_dpp v227, v215, v219, vcc quad_perm:[1,0,3,2] row_mask:0xf bank_mask:0xf
	s_add_u32 s80, s10, 0x20000
	s_addc_u32 s81, s11, 0
	s_add_u32 s82, s10, 0x22000
	s_addc_u32 s83, s11, 0
	global_store_dwordx4 v131, v[220:223], s[80:81]
	global_store_dwordx4 v131, v[224:227], s[82:83]
	v_pk_fma_f32 v[94:95], v[94:95], v[138:139], v[172:173] op_sel_hi:[1,0,1]
	v_pk_fma_f32 v[96:97], v[96:97], v[138:139], v[174:175] op_sel_hi:[1,0,1]
	v_pk_fma_f32 v[90:91], v[90:91], v[138:139], v[176:177] op_sel_hi:[1,0,1]
	v_pk_fma_f32 v[92:93], v[92:93], v[138:139], v[178:179] op_sel_hi:[1,0,1]
	v_max_f32_e32 v94, 0, v94
	v_max_f32_e32 v95, 0, v95
	v_max_f32_e32 v96, 0, v96
	v_max_f32_e32 v97, 0, v97
	v_max_f32_e32 v90, 0, v90
	v_max_f32_e32 v91, 0, v91
	v_max_f32_e32 v92, 0, v92
	v_max_f32_e32 v93, 0, v93
	v_pk_mul_f32 v[94:95], v[94:95], v[94:95]
	v_pk_mul_f32 v[96:97], v[96:97], v[96:97]
	v_pk_mul_f32 v[90:91], v[90:91], v[90:91]
	v_pk_mul_f32 v[92:93], v[92:93], v[92:93]
	v_cvt_pk_bf16_f32 v212, v94, v95
	v_cvt_pk_bf16_f32 v213, v96, v97
	v_cvt_pk_bf16_f32 v214, v90, v91
	v_cvt_pk_bf16_f32 v215, v92, v93
	v_pk_fma_f32 v[86:87], v[86:87], v[138:139], v[186:187] op_sel_hi:[1,0,1]
	v_pk_fma_f32 v[88:89], v[88:89], v[138:139], v[188:189] op_sel_hi:[1,0,1]
	v_pk_fma_f32 v[82:83], v[82:83], v[138:139], v[190:191] op_sel_hi:[1,0,1]
	v_pk_fma_f32 v[84:85], v[84:85], v[138:139], v[192:193] op_sel_hi:[1,0,1]
	v_max_f32_e32 v86, 0, v86
	v_max_f32_e32 v87, 0, v87
	v_max_f32_e32 v88, 0, v88
	v_max_f32_e32 v89, 0, v89
	v_max_f32_e32 v82, 0, v82
	v_max_f32_e32 v83, 0, v83
	v_max_f32_e32 v84, 0, v84
	v_max_f32_e32 v85, 0, v85
	v_pk_mul_f32 v[86:87], v[86:87], v[86:87]
	v_pk_mul_f32 v[88:89], v[88:89], v[88:89]
	v_pk_mul_f32 v[82:83], v[82:83], v[82:83]
	v_pk_mul_f32 v[84:85], v[84:85], v[84:85]
	v_cvt_pk_bf16_f32 v216, v86, v87
	v_cvt_pk_bf16_f32 v217, v88, v89
	v_cvt_pk_bf16_f32 v218, v82, v83
	v_cvt_pk_bf16_f32 v219, v84, v85
	s_mov_b64 vcc, s[66:67]
	v_cndmask_b32_dpp v220, v216, v212, vcc quad_perm:[1,0,3,2] row_mask:0xf bank_mask:0xf
	v_cndmask_b32_dpp v221, v217, v213, vcc quad_perm:[1,0,3,2] row_mask:0xf bank_mask:0xf
	v_cndmask_b32_dpp v222, v218, v214, vcc quad_perm:[1,0,3,2] row_mask:0xf bank_mask:0xf
	v_cndmask_b32_dpp v223, v219, v215, vcc quad_perm:[1,0,3,2] row_mask:0xf bank_mask:0xf
	s_mov_b64 vcc, s[62:63]
	v_cndmask_b32_dpp v224, v212, v216, vcc quad_perm:[1,0,3,2] row_mask:0xf bank_mask:0xf
	v_cndmask_b32_dpp v225, v213, v217, vcc quad_perm:[1,0,3,2] row_mask:0xf bank_mask:0xf
	v_cndmask_b32_dpp v226, v214, v218, vcc quad_perm:[1,0,3,2] row_mask:0xf bank_mask:0xf
	v_cndmask_b32_dpp v227, v215, v219, vcc quad_perm:[1,0,3,2] row_mask:0xf bank_mask:0xf
	s_add_u32 s80, s10, 0x40000
	s_addc_u32 s81, s11, 0
	s_add_u32 s82, s10, 0x42000
	s_addc_u32 s83, s11, 0
	global_store_dwordx4 v131, v[220:223], s[80:81]
	global_store_dwordx4 v131, v[224:227], s[82:83]
	v_pk_fma_f32 v[78:79], v[78:79], v[140:141], v[172:173] op_sel_hi:[1,0,1]
	v_pk_fma_f32 v[80:81], v[80:81], v[140:141], v[174:175] op_sel_hi:[1,0,1]
	v_pk_fma_f32 v[74:75], v[74:75], v[140:141], v[176:177] op_sel_hi:[1,0,1]
	v_pk_fma_f32 v[76:77], v[76:77], v[140:141], v[178:179] op_sel_hi:[1,0,1]
	v_max_f32_e32 v78, 0, v78
	v_max_f32_e32 v79, 0, v79
	v_max_f32_e32 v80, 0, v80
	v_max_f32_e32 v81, 0, v81
	v_max_f32_e32 v74, 0, v74
	v_max_f32_e32 v75, 0, v75
	v_max_f32_e32 v76, 0, v76
	v_max_f32_e32 v77, 0, v77
	v_pk_mul_f32 v[78:79], v[78:79], v[78:79]
	v_pk_mul_f32 v[80:81], v[80:81], v[80:81]
	v_pk_mul_f32 v[74:75], v[74:75], v[74:75]
	v_pk_mul_f32 v[76:77], v[76:77], v[76:77]
	v_cvt_pk_bf16_f32 v212, v78, v79
	v_cvt_pk_bf16_f32 v213, v80, v81
	v_cvt_pk_bf16_f32 v214, v74, v75
	v_cvt_pk_bf16_f32 v215, v76, v77
	v_pk_fma_f32 v[70:71], v[70:71], v[140:141], v[186:187] op_sel_hi:[1,0,1]
	v_pk_fma_f32 v[72:73], v[72:73], v[140:141], v[188:189] op_sel_hi:[1,0,1]
	v_pk_fma_f32 v[66:67], v[66:67], v[140:141], v[190:191] op_sel_hi:[1,0,1]
	v_pk_fma_f32 v[68:69], v[68:69], v[140:141], v[192:193] op_sel_hi:[1,0,1]
	v_max_f32_e32 v70, 0, v70
	v_max_f32_e32 v71, 0, v71
	v_max_f32_e32 v72, 0, v72
	v_max_f32_e32 v73, 0, v73
	v_max_f32_e32 v66, 0, v66
	v_max_f32_e32 v67, 0, v67
	v_max_f32_e32 v68, 0, v68
	v_max_f32_e32 v69, 0, v69
	v_pk_mul_f32 v[70:71], v[70:71], v[70:71]
	v_pk_mul_f32 v[72:73], v[72:73], v[72:73]
	v_pk_mul_f32 v[66:67], v[66:67], v[66:67]
	v_pk_mul_f32 v[68:69], v[68:69], v[68:69]
	v_cvt_pk_bf16_f32 v216, v70, v71
	v_cvt_pk_bf16_f32 v217, v72, v73
	v_cvt_pk_bf16_f32 v218, v66, v67
	v_cvt_pk_bf16_f32 v219, v68, v69
	s_mov_b64 vcc, s[66:67]
	v_cndmask_b32_dpp v220, v216, v212, vcc quad_perm:[1,0,3,2] row_mask:0xf bank_mask:0xf
	v_cndmask_b32_dpp v221, v217, v213, vcc quad_perm:[1,0,3,2] row_mask:0xf bank_mask:0xf
	v_cndmask_b32_dpp v222, v218, v214, vcc quad_perm:[1,0,3,2] row_mask:0xf bank_mask:0xf
	v_cndmask_b32_dpp v223, v219, v215, vcc quad_perm:[1,0,3,2] row_mask:0xf bank_mask:0xf
	s_mov_b64 vcc, s[62:63]
	v_cndmask_b32_dpp v224, v212, v216, vcc quad_perm:[1,0,3,2] row_mask:0xf bank_mask:0xf
	v_cndmask_b32_dpp v225, v213, v217, vcc quad_perm:[1,0,3,2] row_mask:0xf bank_mask:0xf
	v_cndmask_b32_dpp v226, v214, v218, vcc quad_perm:[1,0,3,2] row_mask:0xf bank_mask:0xf
	v_cndmask_b32_dpp v227, v215, v219, vcc quad_perm:[1,0,3,2] row_mask:0xf bank_mask:0xf
	s_add_u32 s80, s10, 0x60000
	s_addc_u32 s81, s11, 0
	s_add_u32 s82, s10, 0x62000
	s_addc_u32 s83, s11, 0
	global_store_dwordx4 v131, v[220:223], s[80:81]
	global_store_dwordx4 v131, v[224:227], s[82:83]
	v_pk_fma_f32 v[62:63], v[62:63], v[142:143], v[172:173] op_sel_hi:[1,0,1]
	v_pk_fma_f32 v[64:65], v[64:65], v[142:143], v[174:175] op_sel_hi:[1,0,1]
	v_pk_fma_f32 v[58:59], v[58:59], v[142:143], v[176:177] op_sel_hi:[1,0,1]
	v_pk_fma_f32 v[60:61], v[60:61], v[142:143], v[178:179] op_sel_hi:[1,0,1]
	v_max_f32_e32 v62, 0, v62
	v_max_f32_e32 v63, 0, v63
	v_max_f32_e32 v64, 0, v64
	v_max_f32_e32 v65, 0, v65
	v_max_f32_e32 v58, 0, v58
	v_max_f32_e32 v59, 0, v59
	v_max_f32_e32 v60, 0, v60
	v_max_f32_e32 v61, 0, v61
	v_pk_mul_f32 v[62:63], v[62:63], v[62:63]
	v_pk_mul_f32 v[64:65], v[64:65], v[64:65]
	v_pk_mul_f32 v[58:59], v[58:59], v[58:59]
	v_pk_mul_f32 v[60:61], v[60:61], v[60:61]
	v_cvt_pk_bf16_f32 v212, v62, v63
	v_cvt_pk_bf16_f32 v213, v64, v65
	v_cvt_pk_bf16_f32 v214, v58, v59
	v_cvt_pk_bf16_f32 v215, v60, v61
	v_pk_fma_f32 v[54:55], v[54:55], v[142:143], v[186:187] op_sel_hi:[1,0,1]
	v_pk_fma_f32 v[56:57], v[56:57], v[142:143], v[188:189] op_sel_hi:[1,0,1]
	v_pk_fma_f32 v[50:51], v[50:51], v[142:143], v[190:191] op_sel_hi:[1,0,1]
	v_pk_fma_f32 v[52:53], v[52:53], v[142:143], v[192:193] op_sel_hi:[1,0,1]
	v_max_f32_e32 v54, 0, v54
	v_max_f32_e32 v55, 0, v55
	v_max_f32_e32 v56, 0, v56
	v_max_f32_e32 v57, 0, v57
	v_max_f32_e32 v50, 0, v50
	v_max_f32_e32 v51, 0, v51
	v_max_f32_e32 v52, 0, v52
	v_max_f32_e32 v53, 0, v53
	v_pk_mul_f32 v[54:55], v[54:55], v[54:55]
	v_pk_mul_f32 v[56:57], v[56:57], v[56:57]
	v_pk_mul_f32 v[50:51], v[50:51], v[50:51]
	v_pk_mul_f32 v[52:53], v[52:53], v[52:53]
	v_cvt_pk_bf16_f32 v216, v54, v55
	v_cvt_pk_bf16_f32 v217, v56, v57
	v_cvt_pk_bf16_f32 v218, v50, v51
	v_cvt_pk_bf16_f32 v219, v52, v53
	s_mov_b64 vcc, s[66:67]
	v_cndmask_b32_dpp v220, v216, v212, vcc quad_perm:[1,0,3,2] row_mask:0xf bank_mask:0xf
	v_cndmask_b32_dpp v221, v217, v213, vcc quad_perm:[1,0,3,2] row_mask:0xf bank_mask:0xf
	v_cndmask_b32_dpp v222, v218, v214, vcc quad_perm:[1,0,3,2] row_mask:0xf bank_mask:0xf
	v_cndmask_b32_dpp v223, v219, v215, vcc quad_perm:[1,0,3,2] row_mask:0xf bank_mask:0xf
	s_mov_b64 vcc, s[62:63]
	v_cndmask_b32_dpp v224, v212, v216, vcc quad_perm:[1,0,3,2] row_mask:0xf bank_mask:0xf
	v_cndmask_b32_dpp v225, v213, v217, vcc quad_perm:[1,0,3,2] row_mask:0xf bank_mask:0xf
	v_cndmask_b32_dpp v226, v214, v218, vcc quad_perm:[1,0,3,2] row_mask:0xf bank_mask:0xf
	v_cndmask_b32_dpp v227, v215, v219, vcc quad_perm:[1,0,3,2] row_mask:0xf bank_mask:0xf
	s_add_u32 s80, s10, 0x100000
	s_addc_u32 s81, s11, 0
	s_add_u32 s82, s10, 0x102000
	s_addc_u32 s83, s11, 0
	global_store_dwordx4 v131, v[220:223], s[80:81]
	global_store_dwordx4 v131, v[224:227], s[82:83]
	v_pk_fma_f32 v[46:47], v[46:47], v[144:145], v[172:173] op_sel_hi:[1,0,1]
	v_pk_fma_f32 v[48:49], v[48:49], v[144:145], v[174:175] op_sel_hi:[1,0,1]
	v_pk_fma_f32 v[42:43], v[42:43], v[144:145], v[176:177] op_sel_hi:[1,0,1]
	v_pk_fma_f32 v[44:45], v[44:45], v[144:145], v[178:179] op_sel_hi:[1,0,1]
	v_max_f32_e32 v46, 0, v46
	v_max_f32_e32 v47, 0, v47
	v_max_f32_e32 v48, 0, v48
	v_max_f32_e32 v49, 0, v49
	v_max_f32_e32 v42, 0, v42
	v_max_f32_e32 v43, 0, v43
	v_max_f32_e32 v44, 0, v44
	v_max_f32_e32 v45, 0, v45
	v_pk_mul_f32 v[46:47], v[46:47], v[46:47]
	v_pk_mul_f32 v[48:49], v[48:49], v[48:49]
	v_pk_mul_f32 v[42:43], v[42:43], v[42:43]
	v_pk_mul_f32 v[44:45], v[44:45], v[44:45]
	v_cvt_pk_bf16_f32 v212, v46, v47
	v_cvt_pk_bf16_f32 v213, v48, v49
	v_cvt_pk_bf16_f32 v214, v42, v43
	v_cvt_pk_bf16_f32 v215, v44, v45
	v_pk_fma_f32 v[38:39], v[38:39], v[144:145], v[186:187] op_sel_hi:[1,0,1]
	v_pk_fma_f32 v[40:41], v[40:41], v[144:145], v[188:189] op_sel_hi:[1,0,1]
	v_pk_fma_f32 v[34:35], v[34:35], v[144:145], v[190:191] op_sel_hi:[1,0,1]
	v_pk_fma_f32 v[36:37], v[36:37], v[144:145], v[192:193] op_sel_hi:[1,0,1]
	v_max_f32_e32 v38, 0, v38
	v_max_f32_e32 v39, 0, v39
	v_max_f32_e32 v40, 0, v40
	v_max_f32_e32 v41, 0, v41
	v_max_f32_e32 v34, 0, v34
	v_max_f32_e32 v35, 0, v35
	v_max_f32_e32 v36, 0, v36
	v_max_f32_e32 v37, 0, v37
	v_pk_mul_f32 v[38:39], v[38:39], v[38:39]
	v_pk_mul_f32 v[40:41], v[40:41], v[40:41]
	v_pk_mul_f32 v[34:35], v[34:35], v[34:35]
	v_pk_mul_f32 v[36:37], v[36:37], v[36:37]
	v_cvt_pk_bf16_f32 v216, v38, v39
	v_cvt_pk_bf16_f32 v217, v40, v41
	v_cvt_pk_bf16_f32 v218, v34, v35
	v_cvt_pk_bf16_f32 v219, v36, v37
	s_mov_b64 vcc, s[66:67]
	v_cndmask_b32_dpp v220, v216, v212, vcc quad_perm:[1,0,3,2] row_mask:0xf bank_mask:0xf
	v_cndmask_b32_dpp v221, v217, v213, vcc quad_perm:[1,0,3,2] row_mask:0xf bank_mask:0xf
	v_cndmask_b32_dpp v222, v218, v214, vcc quad_perm:[1,0,3,2] row_mask:0xf bank_mask:0xf
	v_cndmask_b32_dpp v223, v219, v215, vcc quad_perm:[1,0,3,2] row_mask:0xf bank_mask:0xf
	s_mov_b64 vcc, s[62:63]
	v_cndmask_b32_dpp v224, v212, v216, vcc quad_perm:[1,0,3,2] row_mask:0xf bank_mask:0xf
	v_cndmask_b32_dpp v225, v213, v217, vcc quad_perm:[1,0,3,2] row_mask:0xf bank_mask:0xf
	v_cndmask_b32_dpp v226, v214, v218, vcc quad_perm:[1,0,3,2] row_mask:0xf bank_mask:0xf
	v_cndmask_b32_dpp v227, v215, v219, vcc quad_perm:[1,0,3,2] row_mask:0xf bank_mask:0xf
	s_add_u32 s80, s10, 0x120000
	s_addc_u32 s81, s11, 0
	s_add_u32 s82, s10, 0x122000
	s_addc_u32 s83, s11, 0
	global_store_dwordx4 v131, v[220:223], s[80:81]
	global_store_dwordx4 v131, v[224:227], s[82:83]
	v_pk_fma_f32 v[30:31], v[30:31], v[168:169], v[172:173] op_sel_hi:[1,0,1]
	v_pk_fma_f32 v[32:33], v[32:33], v[168:169], v[174:175] op_sel_hi:[1,0,1]
	v_pk_fma_f32 v[26:27], v[26:27], v[168:169], v[176:177] op_sel_hi:[1,0,1]
	v_pk_fma_f32 v[28:29], v[28:29], v[168:169], v[178:179] op_sel_hi:[1,0,1]
	v_max_f32_e32 v30, 0, v30
	v_max_f32_e32 v31, 0, v31
	v_max_f32_e32 v32, 0, v32
	v_max_f32_e32 v33, 0, v33
	v_max_f32_e32 v26, 0, v26
	v_max_f32_e32 v27, 0, v27
	v_max_f32_e32 v28, 0, v28
	v_max_f32_e32 v29, 0, v29
	v_pk_mul_f32 v[30:31], v[30:31], v[30:31]
	v_pk_mul_f32 v[32:33], v[32:33], v[32:33]
	v_pk_mul_f32 v[26:27], v[26:27], v[26:27]
	v_pk_mul_f32 v[28:29], v[28:29], v[28:29]
	v_cvt_pk_bf16_f32 v212, v30, v31
	v_cvt_pk_bf16_f32 v213, v32, v33
	v_cvt_pk_bf16_f32 v214, v26, v27
	v_cvt_pk_bf16_f32 v215, v28, v29
	v_pk_fma_f32 v[22:23], v[22:23], v[168:169], v[186:187] op_sel_hi:[1,0,1]
	v_pk_fma_f32 v[24:25], v[24:25], v[168:169], v[188:189] op_sel_hi:[1,0,1]
	v_pk_fma_f32 v[18:19], v[18:19], v[168:169], v[190:191] op_sel_hi:[1,0,1]
	v_pk_fma_f32 v[20:21], v[20:21], v[168:169], v[192:193] op_sel_hi:[1,0,1]
	v_max_f32_e32 v22, 0, v22
	v_max_f32_e32 v23, 0, v23
	v_max_f32_e32 v24, 0, v24
	v_max_f32_e32 v25, 0, v25
	v_max_f32_e32 v18, 0, v18
	v_max_f32_e32 v19, 0, v19
	v_max_f32_e32 v20, 0, v20
	v_max_f32_e32 v21, 0, v21
	v_pk_mul_f32 v[22:23], v[22:23], v[22:23]
	v_pk_mul_f32 v[24:25], v[24:25], v[24:25]
	v_pk_mul_f32 v[18:19], v[18:19], v[18:19]
	v_pk_mul_f32 v[20:21], v[20:21], v[20:21]
	v_cvt_pk_bf16_f32 v216, v22, v23
	v_cvt_pk_bf16_f32 v217, v24, v25
	v_cvt_pk_bf16_f32 v218, v18, v19
	v_cvt_pk_bf16_f32 v219, v20, v21
	s_mov_b64 vcc, s[66:67]
	v_cndmask_b32_dpp v220, v216, v212, vcc quad_perm:[1,0,3,2] row_mask:0xf bank_mask:0xf
	v_cndmask_b32_dpp v221, v217, v213, vcc quad_perm:[1,0,3,2] row_mask:0xf bank_mask:0xf
	v_cndmask_b32_dpp v222, v218, v214, vcc quad_perm:[1,0,3,2] row_mask:0xf bank_mask:0xf
	v_cndmask_b32_dpp v223, v219, v215, vcc quad_perm:[1,0,3,2] row_mask:0xf bank_mask:0xf
	s_mov_b64 vcc, s[62:63]
	v_cndmask_b32_dpp v224, v212, v216, vcc quad_perm:[1,0,3,2] row_mask:0xf bank_mask:0xf
	v_cndmask_b32_dpp v225, v213, v217, vcc quad_perm:[1,0,3,2] row_mask:0xf bank_mask:0xf
	v_cndmask_b32_dpp v226, v214, v218, vcc quad_perm:[1,0,3,2] row_mask:0xf bank_mask:0xf
	v_cndmask_b32_dpp v227, v215, v219, vcc quad_perm:[1,0,3,2] row_mask:0xf bank_mask:0xf
	s_add_u32 s80, s10, 0x140000
	s_addc_u32 s81, s11, 0
	s_add_u32 s82, s10, 0x142000
	s_addc_u32 s83, s11, 0
	global_store_dwordx4 v131, v[220:223], s[80:81]
	global_store_dwordx4 v131, v[224:227], s[82:83]
	v_pk_fma_f32 v[14:15], v[14:15], v[170:171], v[172:173] op_sel_hi:[1,0,1]
	v_pk_fma_f32 v[16:17], v[16:17], v[170:171], v[174:175] op_sel_hi:[1,0,1]
	v_pk_fma_f32 v[10:11], v[10:11], v[170:171], v[176:177] op_sel_hi:[1,0,1]
	v_pk_fma_f32 v[12:13], v[12:13], v[170:171], v[178:179] op_sel_hi:[1,0,1]
	v_max_f32_e32 v14, 0, v14
	v_max_f32_e32 v15, 0, v15
	v_max_f32_e32 v16, 0, v16
	v_max_f32_e32 v17, 0, v17
	v_max_f32_e32 v10, 0, v10
	v_max_f32_e32 v11, 0, v11
	v_max_f32_e32 v12, 0, v12
	v_max_f32_e32 v13, 0, v13
	v_pk_mul_f32 v[14:15], v[14:15], v[14:15]
	v_pk_mul_f32 v[16:17], v[16:17], v[16:17]
	v_pk_mul_f32 v[10:11], v[10:11], v[10:11]
	v_pk_mul_f32 v[12:13], v[12:13], v[12:13]
	v_cvt_pk_bf16_f32 v212, v14, v15
	v_cvt_pk_bf16_f32 v213, v16, v17
	v_cvt_pk_bf16_f32 v214, v10, v11
	v_cvt_pk_bf16_f32 v215, v12, v13
	v_pk_fma_f32 v[6:7], v[6:7], v[170:171], v[186:187] op_sel_hi:[1,0,1]
	v_pk_fma_f32 v[8:9], v[8:9], v[170:171], v[188:189] op_sel_hi:[1,0,1]
	v_pk_fma_f32 v[2:3], v[2:3], v[170:171], v[190:191] op_sel_hi:[1,0,1]
	v_pk_fma_f32 v[4:5], v[4:5], v[170:171], v[192:193] op_sel_hi:[1,0,1]
	v_max_f32_e32 v6, 0, v6
	v_max_f32_e32 v7, 0, v7
	v_max_f32_e32 v8, 0, v8
	v_max_f32_e32 v9, 0, v9
	v_max_f32_e32 v2, 0, v2
	v_max_f32_e32 v3, 0, v3
	v_max_f32_e32 v4, 0, v4
	v_max_f32_e32 v5, 0, v5
	v_pk_mul_f32 v[6:7], v[6:7], v[6:7]
	v_pk_mul_f32 v[8:9], v[8:9], v[8:9]
	v_pk_mul_f32 v[2:3], v[2:3], v[2:3]
	v_pk_mul_f32 v[4:5], v[4:5], v[4:5]
	v_cvt_pk_bf16_f32 v216, v6, v7
	v_cvt_pk_bf16_f32 v217, v8, v9
	v_cvt_pk_bf16_f32 v218, v2, v3
	v_cvt_pk_bf16_f32 v219, v4, v5
	s_mov_b64 vcc, s[66:67]
	v_cndmask_b32_dpp v220, v216, v212, vcc quad_perm:[1,0,3,2] row_mask:0xf bank_mask:0xf
	v_cndmask_b32_dpp v221, v217, v213, vcc quad_perm:[1,0,3,2] row_mask:0xf bank_mask:0xf
	v_cndmask_b32_dpp v222, v218, v214, vcc quad_perm:[1,0,3,2] row_mask:0xf bank_mask:0xf
	v_cndmask_b32_dpp v223, v219, v215, vcc quad_perm:[1,0,3,2] row_mask:0xf bank_mask:0xf
	s_mov_b64 vcc, s[62:63]
	v_cndmask_b32_dpp v224, v212, v216, vcc quad_perm:[1,0,3,2] row_mask:0xf bank_mask:0xf
	v_cndmask_b32_dpp v225, v213, v217, vcc quad_perm:[1,0,3,2] row_mask:0xf bank_mask:0xf
	v_cndmask_b32_dpp v226, v214, v218, vcc quad_perm:[1,0,3,2] row_mask:0xf bank_mask:0xf
	v_cndmask_b32_dpp v227, v215, v219, vcc quad_perm:[1,0,3,2] row_mask:0xf bank_mask:0xf
	s_add_u32 s80, s10, 0x160000
	s_addc_u32 s81, s11, 0
	s_add_u32 s82, s10, 0x162000
	s_addc_u32 s83, s11, 0
	global_store_dwordx4 v131, v[220:223], s[80:81]
	global_store_dwordx4 v131, v[224:227], s[82:83]
	s_mov_b32 s19, 0x160000
	s_lshl_b32 s21, s41, 2
	s_mov_b64 s[26:27], 0x160000
	s_andn2_b64 vcc, exec, s[12:13]
	s_mov_b64 s[12:13], -1
	s_cbranch_vccnz .LBB0_1383
	s_andn2_b64 vcc, exec, s[0:1]
	s_cbranch_vccnz .LBB0_1382
	s_barrier
	s_branch .LBB0_1382
